# RESID epilogue: nt (streaming) hint on the f32 residual-stream row stores
# speedup vs baseline: 1.0156x; 1.0003x over previous
; DI int crow(int i, int hh) { return (i & 3) + 8 * (i >> 2) + 4 * hh; }
; DI void epi_slab(const GemmCfg c, const f32x16 (&acc)[4], float* sW, const float* rss, const size_t row0, const int g, const int lane,
;                  float* const g_h, u16* const g_hb, float* const g_out, const int final_out) {
;   int ln_ = lane;
;   asm volatile("" : "+v"(ln_));
;   const int l31 = ln_ & 31, hh = ln_ >> 5;
; #pragma unroll
;   for (int nb = 0; nb < 4; ++nb)
; #pragma unroll
;     for (int i = 0; i < 16; ++i) sW[crow(i, hh) * 132 + nb * 32 + l31] = acc[nb][i];
;   asm volatile("s_waitcnt lgkmcnt(0)" ::: "memory");
;   const int K = c.K;
;   const float invK = 1.0f / (float)K;
;   if (c.epi == EPI_SWIGLU) {
; DI void gemm_run(const GemmCfg c, char* smem, float* const g_h, u16* const g_hb, float* const g_out, const int final_out) {
;     ...
;     __syncthreads();
; #pragma unroll
;     for (int mb = 0; mb < 2; ++mb) {
;       const size_t row0 = (size_t)tm * 256 + wm * 64 + mb * 32;
;       if (row0 < (size_t)M) epi_slab(c, acc[mb], sW, s_rowss + wm * 64 + mb * 32, row0, tn * 2 + wn, lane, g_h, g_hb, g_out, final_out);
.LBB0_124:
	s_ashr_i32 s79, s78, 31
	s_lshl_b64 s[4:5], s[78:79], 8
	s_add_u32 s6, s4, s86
	s_addc_u32 s7, s5, s87
	s_lshl_b32 s1, s49, 1
	s_or_b32 s8, s1, s75
	s_lshl_b32 s64, s8, 7
	s_cmp_gt_i32 s8, 1
	s_cselect_b64 s[84:85], -1, 0
	s_cmp_gt_u32 s1, 3
	s_cselect_b64 s[26:27], -1, 0
	s_cmp_eq_u32 s8, 4
	s_cselect_b64 s[70:71], -1, 0
	s_cmp_lt_i32 s8, s20
	s_cselect_b64 s[72:73], -1, 0
	s_cmp_lt_i32 s8, 8
	s_cselect_b64 vcc, -1, 0
	v_mov_b32_e32 v128, 0x3e38aa3b
	v_cndmask_b32_e32 v130, 1.0, v128, vcc
	s_and_b64 s[8:9], vcc, exec
	s_waitcnt lgkmcnt(0)
	v_mov_b64_e32 v[128:129], 0x4080
	s_cselect_b32 s8, 0, 0x100
	v_cmp_lt_u64_e64 s[44:45], s[6:7], v[128:129]
	v_mov_b64_e32 v[128:129], 0x407f
	s_add_u32 s58, s66, s8
	v_cmp_gt_u64_e32 vcc, s[6:7], v[128:129]
	s_addc_u32 s59, s67, 0
	s_barrier
	s_cbranch_vccnz .LBB0_279
	s_cmp_eq_u32 s52, 2
	s_cbranch_scc1 .Lqkv2
	s_cmp_eq_u32 s52, 5
	s_cbranch_scc1 .Lqabs2
	s_cmp_eq_u32 s52, 4
	s_cbranch_scc1 .Lqidx2
	s_cmp_eq_u32 s52, 6
	s_cbranch_scc1 .Lplain2
	s_cmp_eq_u32 s52, 0
	s_cbranch_scc1 .Lswg2
	v_mov_b32_e32 v131, v185
	s_movk_i32 s8, 0x210
	v_ashrrev_i32_e32 v128, 5, v131
	v_and_b32_e32 v132, 31, v131
	v_mul_lo_u32 v133, v128, s8
	v_lshlrev_b32_e32 v129, 2, v132
	v_lshlrev_b32_e32 v134, 2, v133
	v_add3_u32 v129, s53, v129, v134
	v_lshrrev_b32_e32 v242, 4, v131
	v_mul_u32_u24_e32 v242, 0x840, v242
	v_and_b32_e32 v243, 15, v131
	v_lshl_add_u32 v242, v243, 2, v242
	v_add_u32_e32 v234, s53, v242
	v_add_u32_e32 v235, 0x210, v234
	v_add_u32_e32 v236, 0x420, v234
	v_add_u32_e32 v237, 0x630, v234
	v_add_u32_e32 v238, 0x2100, v234
	v_add_u32_e32 v239, 0x2310, v234
	v_add_u32_e32 v240, 0x2520, v234
	v_add_u32_e32 v241, 0x2730, v234
	ds_write2_b32 v234, v64, v68 offset1:16
	ds_write2_b32 v234, v72, v76 offset0:32 offset1:48
	ds_write2_b32 v234, v80, v84 offset0:64 offset1:80
	ds_write2_b32 v234, v88, v92 offset0:96 offset1:112
	ds_write2_b32 v235, v65, v69 offset1:16
	ds_write2_b32 v235, v73, v77 offset0:32 offset1:48
	ds_write2_b32 v235, v81, v85 offset0:64 offset1:80
	ds_write2_b32 v235, v89, v93 offset0:96 offset1:112
	ds_write2_b32 v236, v66, v70 offset1:16
	ds_write2_b32 v236, v74, v78 offset0:32 offset1:48
	ds_write2_b32 v236, v82, v86 offset0:64 offset1:80
	ds_write2_b32 v236, v90, v94 offset0:96 offset1:112
	ds_write2_b32 v237, v67, v71 offset1:16
	ds_write2_b32 v237, v75, v79 offset0:32 offset1:48
	ds_write2_b32 v237, v83, v87 offset0:64 offset1:80
	ds_write2_b32 v237, v91, v95 offset0:96 offset1:112
	ds_write2_b32 v238, v96, v100 offset1:16
	ds_write2_b32 v238, v104, v108 offset0:32 offset1:48
	ds_write2_b32 v238, v112, v116 offset0:64 offset1:80
	ds_write2_b32 v238, v120, v124 offset0:96 offset1:112
	ds_write2_b32 v239, v97, v101 offset1:16
	ds_write2_b32 v239, v105, v109 offset0:32 offset1:48
	ds_write2_b32 v239, v113, v117 offset0:64 offset1:80
	ds_write2_b32 v239, v121, v125 offset0:96 offset1:112
	ds_write2_b32 v240, v98, v102 offset1:16
	ds_write2_b32 v240, v106, v110 offset0:32 offset1:48
	ds_write2_b32 v240, v114, v118 offset0:64 offset1:80
	ds_write2_b32 v240, v122, v126 offset0:96 offset1:112
	ds_write2_b32 v241, v99, v103 offset1:16
	ds_write2_b32 v241, v107, v111 offset0:32 offset1:48
	ds_write2_b32 v241, v115, v119 offset0:64 offset1:80
	ds_write2_b32 v241, v123, v127 offset0:96 offset1:112
	v_add_u32_e32 v64, 0x3800, v129
	v_add_u32_e32 v65, 0x1000, v129
	v_add_u32_e32 v66, 0x1400, v129
	v_add_u32_e32 v67, 0x2000, v129
	v_add_u32_e32 v68, 0x2400, v129
	v_add_u32_e32 v70, 0x3400, v129
	v_add_u32_e32 v69, 0x3000, v129
	v_add_u32_e32 v71, 0x3600, v129
	s_waitcnt lgkmcnt(0)
	s_mov_b64 s[22:23], -1
	s_mov_b64 s[50:51], 0
	s_cmp_lt_i32 s52, 1
	s_mov_b64 s[14:15], 0
	s_cbranch_scc1 .LBB0_272
	s_cmp_eq_u32 s52, 1
	s_mov_b64 s[14:15], -1
	s_cbranch_scc0 .LBB0_192
; DI void epi_slab(const GemmCfg c, const f32x16 (&acc)[4], float* sW, const float* rss, const size_t row0, const int g, const int lane,
;                  float* const g_h, u16* const g_hb, float* const g_out, const int final_out) {
;     ...
;     for (int hb_ = 0; hb_ < 2; ++hb_) {
;       f32x4 hv[8];
; #pragma unroll
;       for (int i8 = 0; i8 < 8; ++i8) hv[i8] = *(const f32x4*)(g_h + (row0 + hh + 2 * (hb_ * 8 + i8)) * D + col);
; #pragma unroll
;       for (int i8 = 0; i8 < 8; ++i8) {
;         const int r = hh + 2 * (hb_ * 8 + i8);
;         const size_t row = row0 + r;
;         f32x4 v = *(const f32x4*)(sW + r * 132 + c4);
;         f32x4 o = hv[i8] + v * sc;
;         *(f32x4*)(g_h + row * D + col) = o;
;         *(u32x2*)(g_hb + row * D + col) = MK2(pack2(o[0], o[1]), pack2(o[2], o[3]));
;         if (final_out) {
;           const int b = (int)(row / T), t = (int)(row % T);
;           if (t >= 16) *(f32x4*)(g_out + ((size_t)b * 2048 + (t - 16)) * D + col) = o;
;         }
	v_lshl_or_b32 v98, v132, 2, s64
	v_ashrrev_i32_e32 v129, 31, v128
	v_ashrrev_i32_e32 v99, 31, v98
	v_readlane_b32 s8, v254, 60
	v_lshl_add_u64 v[104:105], s[6:7], 0, v[128:129]
	v_lshlrev_b64 v[106:107], 2, v[98:99]
	v_readlane_b32 s9, v254, 61
	v_lshlrev_b64 v[64:65], 12, v[104:105]
	v_lshl_add_u32 v108, v132, 4, s53
	v_lshl_add_u64 v[96:97], s[8:9], 0, v[106:107]
	v_lshl_add_u64 v[102:103], v[96:97], 0, v[64:65]
	s_movk_i32 s8, 0x2000
	v_add_co_u32_e32 v64, vcc, s8, v102
	s_movk_i32 s8, 0x4000
	s_nop 0
	v_addc_co_u32_e32 v65, vcc, 0, v103, vcc
	global_load_dwordx4 v[92:95], v[102:103], off
	global_load_dwordx4 v[88:91], v[64:65], off
	v_add_co_u32_e32 v64, vcc, s8, v102
	s_movk_i32 s8, 0x6000
	s_nop 0
	v_addc_co_u32_e32 v65, vcc, 0, v103, vcc
	v_add_co_u32_e32 v66, vcc, s8, v102
	s_mov_b32 s8, 0x8000
	s_nop 0
	v_addc_co_u32_e32 v67, vcc, 0, v103, vcc
	global_load_dwordx4 v[84:87], v[64:65], off
	global_load_dwordx4 v[80:83], v[66:67], off
	v_add_co_u32_e32 v64, vcc, s8, v102
	s_mov_b32 s8, 0xa000
	s_nop 0
	v_addc_co_u32_e32 v65, vcc, 0, v103, vcc
	v_add_co_u32_e32 v66, vcc, s8, v102
	s_mov_b32 s8, 0xc000
	s_nop 0
	v_addc_co_u32_e32 v67, vcc, 0, v103, vcc
	global_load_dwordx4 v[76:79], v[64:65], off
	global_load_dwordx4 v[72:75], v[66:67], off
	v_add_co_u32_e32 v64, vcc, s8, v102
	s_mov_b32 s8, 0xe000
	s_nop 0
	v_addc_co_u32_e32 v65, vcc, 0, v103, vcc
	v_add_co_u32_e32 v66, vcc, s8, v102
	v_add_u32_e32 v100, v108, v133
	s_nop 0
	v_addc_co_u32_e32 v67, vcc, 0, v103, vcc
	global_load_dwordx4 v[68:71], v[64:65], off
	s_nop 0
	global_load_dwordx4 v[64:67], v[66:67], off
	v_readlane_b32 s8, v255, 3
	ds_read_b128 v[110:113], v100
	v_readlane_b32 s9, v255, 4
	v_mov_b32_e32 v171, v170
	s_waitcnt vmcnt(7) lgkmcnt(0)
	v_pk_fma_f32 v[94:95], v[170:171], v[112:113], v[94:95]
	v_lshl_add_u64 v[100:101], v[98:99], 1, s[8:9]
	v_mov_b32_e32 v148, 0x11f69000
	v_mov_b32_e32 v149, 0
	v_lshl_add_u64 v[146:147], v[148:149], 0, s[8:9]
	v_lshrrev_b32_e32 v148, 6, v98
	v_lshlrev_b32_e32 v148, 2, v148
	v_lshl_add_u64 v[146:147], v[146:147], 0, v[148:149]
	v_mov_b32_e32 v143, 0
	v_readlane_b32 s8, v252, 47
	v_readlane_b32 s9, v252, 48
	v_readlane_b32 s8, v255, 13
	v_readlane_b32 s9, v255, 14
	v_readlane_b32 s22, v252, 61
	v_readlane_b32 s23, v252, 62
	v_pk_fma_f32 v[92:93], v[172:173], v[110:111], v[92:93]
	v_lshlrev_b64 v[110:111], 11, v[104:105]
	v_cndmask_b32_e64 v109, 0, 1, s[8:9]
	v_lshl_add_u64 v[98:99], s[22:23], 0, v[106:107]
	v_cvt_pk_bf16_f32 v106, v92, v93
	v_cvt_pk_bf16_f32 v107, v94, v95
	v_lshrrev_b32_e32 v142, 5, v110
	v_lshl_add_u64 v[110:111], v[100:101], 0, v[110:111]
	v_cmp_ne_u32_e64 s[46:47], 1, v109
	s_andn2_b64 vcc, exec, s[8:9]
	v_readlane_b32 s10, v252, 49
	v_readlane_b32 s11, v252, 50
	v_readlane_b32 s12, v252, 51
	v_readlane_b32 s13, v252, 52
	v_readlane_b32 s14, v252, 53
	v_readlane_b32 s15, v252, 54
	v_readlane_b32 s16, v252, 55
	v_readlane_b32 s17, v252, 56
	v_readlane_b32 s18, v252, 57
	v_readlane_b32 s19, v252, 58
	v_readlane_b32 s20, v252, 59
	v_readlane_b32 s21, v252, 60
	global_store_dwordx4 v[102:103], v[92:95], off nt
	global_store_dwordx2 v[110:111], v[106:107], off
	v_mov_b32_e32 v141, 0
	v_dot2c_f32_bf16_e32 v141, v106, v106
	v_dot2c_f32_bf16_e32 v141, v107, v107
	s_nop 4
	v_add_f32_dpp v141, v141, v141 quad_perm:[1,0,3,2] row_mask:0xf bank_mask:0xf
	s_nop 1
	v_add_f32_dpp v141, v141, v141 quad_perm:[2,3,0,1] row_mask:0xf bank_mask:0xf
	s_nop 1
	v_add_f32_dpp v141, v141, v141 row_half_mirror row_mask:0xf bank_mask:0xf
	s_nop 1
	v_add_f32_dpp v141, v141, v141 row_mirror row_mask:0xf bank_mask:0xf
	v_lshl_add_u64 v[144:145], v[142:143], 0, v[146:147]
	global_store_dword v[144:145], v141, off
	s_cbranch_vccnz .LBB0_131
	s_mov_b32 s8, 0xe03f80ff
	v_mul_hi_u32 v164, v104, s8
	v_mad_u64_u32 v[106:107], s[14:15], v105, s8, v[164:165]
	v_mov_b32_e32 v164, v107
	v_mov_b32_e32 v107, v165
	s_mov_b32 s8, 0xfe03f80f
	v_mad_u64_u32 v[106:107], s[14:15], v104, s8, v[106:107]
	v_mov_b32_e32 v106, v107
	v_mov_b32_e32 v107, v165
	v_lshl_add_u64 v[106:107], v[164:165], 0, v[106:107]
	v_mad_u64_u32 v[106:107], s[14:15], v105, s8, v[106:107]
	v_alignbit_b32 v109, v107, v106, 11
	s_movk_i32 s8, 0x810
	v_mad_u64_u32 v[110:111], s[14:15], v109, s8, 0
	v_lshrrev_b32_e32 v109, 11, v107
	v_mad_u32_u24 v109, v109, s8, v111
	v_sub_co_u32_e32 v104, vcc, v104, v110
	s_nop 1
	v_subb_co_u32_e32 v105, vcc, v105, v109, vcc
	v_cmp_lt_u64_e32 vcc, 15, v[104:105]
	s_and_saveexec_b64 s[14:15], vcc
	s_cbranch_execz .LBB0_130
	v_lshrrev_b64 v[106:107], 11, v[106:107]
	v_mov_b32_e32 v110, v165
	v_mov_b32_e32 v111, v106
	v_ashrrev_i64 v[106:107], 21, v[110:111]
	v_add_u32_e32 v164, -16, v104
	v_lshl_add_u64 v[104:105], v[106:107], 0, v[164:165]
	v_lshlrev_b64 v[104:105], 12, v[104:105]
	v_lshl_add_u64 v[104:105], v[98:99], 0, v[104:105]
	global_store_dwordx4 v[104:105], v[92:95], off

; DI void epi_slab(const GemmCfg c, const f32x16 (&acc)[4], float* sW, const float* rss, const size_t row0, const int g, const int lane,
;                  float* const g_h, u16* const g_hb, float* const g_out, const int final_out) {
;     ...
;     for (int hb_ = 0; hb_ < 2; ++hb_) {
;       f32x4 hv[8];
; #pragma unroll
;       for (int i8 = 0; i8 < 8; ++i8) hv[i8] = *(const f32x4*)(g_h + (row0 + hh + 2 * (hb_ * 8 + i8)) * D + col);
; #pragma unroll
;       for (int i8 = 0; i8 < 8; ++i8) {
;         const int r = hh + 2 * (hb_ * 8 + i8);
;         const size_t row = row0 + r;
;         f32x4 v = *(const f32x4*)(sW + r * 132 + c4);
;         f32x4 o = hv[i8] + v * sc;
;         *(f32x4*)(g_h + row * D + col) = o;
;         *(u32x2*)(g_hb + row * D + col) = MK2(pack2(o[0], o[1]), pack2(o[2], o[3]));
;         if (final_out) {
;           const int b = (int)(row / T), t = (int)(row % T);
;           if (t >= 16) *(f32x4*)(g_out + ((size_t)b * 2048 + (t - 16)) * D + col) = o;
;         }
.LBB0_135:
	ds_read_b128 v[90:93], v106 offset:1056
	v_add_u32_e32 v88, 4, v128
	v_ashrrev_i32_e32 v89, 31, v88
	v_lshl_add_u64 v[88:89], s[6:7], 0, v[88:89]
	v_mov_b32_e32 v171, v170
	s_waitcnt vmcnt(11) lgkmcnt(0)
	v_pk_fma_f32 v[84:85], v[172:173], v[90:91], v[84:85]
	v_lshlrev_b64 v[90:91], 12, v[88:89]
	v_pk_fma_f32 v[86:87], v[170:171], v[92:93], v[86:87]
	v_lshl_add_u64 v[90:91], v[96:97], 0, v[90:91]
	v_lshlrev_b64 v[92:93], 11, v[88:89]
	global_store_dwordx4 v[90:91], v[84:87], off nt
	v_cvt_pk_bf16_f32 v90, v84, v85
	v_cvt_pk_bf16_f32 v91, v86, v87
	v_lshrrev_b32_e32 v142, 5, v92
	v_lshl_add_u64 v[92:93], v[100:101], 0, v[92:93]
	s_and_b64 vcc, exec, s[46:47]
	global_store_dwordx2 v[92:93], v[90:91], off
	v_mov_b32_e32 v141, 0
	v_dot2c_f32_bf16_e32 v141, v90, v90
	v_dot2c_f32_bf16_e32 v141, v91, v91
	s_nop 4
	v_add_f32_dpp v141, v141, v141 quad_perm:[1,0,3,2] row_mask:0xf bank_mask:0xf
	s_nop 1
	v_add_f32_dpp v141, v141, v141 quad_perm:[2,3,0,1] row_mask:0xf bank_mask:0xf
	s_nop 1
	v_add_f32_dpp v141, v141, v141 row_half_mirror row_mask:0xf bank_mask:0xf
	s_nop 1
	v_add_f32_dpp v141, v141, v141 row_mirror row_mask:0xf bank_mask:0xf
	v_lshl_add_u64 v[144:145], v[142:143], 0, v[146:147]
	global_store_dword v[144:145], v141, off
	s_cbranch_vccnz .LBB0_139
	s_mov_b32 s8, 0xe03f80ff
	v_mul_hi_u32 v164, v88, s8
	v_mad_u64_u32 v[90:91], s[14:15], v89, s8, v[164:165]
	v_mov_b32_e32 v164, v91
	v_mov_b32_e32 v91, v165
	s_mov_b32 s8, 0xfe03f80f
	v_mad_u64_u32 v[90:91], s[14:15], v88, s8, v[90:91]
	v_mov_b32_e32 v90, v91
	v_mov_b32_e32 v91, v165
	v_lshl_add_u64 v[90:91], v[164:165], 0, v[90:91]
	v_mad_u64_u32 v[90:91], s[14:15], v89, s8, v[90:91]
	v_alignbit_b32 v92, v91, v90, 11
	s_movk_i32 s8, 0x810
	v_mad_u64_u32 v[92:93], s[14:15], v92, s8, 0
	v_lshrrev_b32_e32 v94, 11, v91
	v_mad_u32_u24 v93, v94, s8, v93
	v_sub_co_u32_e32 v88, vcc, v88, v92
	s_nop 1
	v_subb_co_u32_e32 v89, vcc, v89, v93, vcc
	v_cmp_lt_u64_e32 vcc, 15, v[88:89]
	s_and_saveexec_b64 s[14:15], vcc
	s_cbranch_execz .LBB0_138
	v_lshrrev_b64 v[90:91], 11, v[90:91]
	v_mov_b32_e32 v92, v165
	v_mov_b32_e32 v93, v90
	v_ashrrev_i64 v[90:91], 21, v[92:93]
	v_add_u32_e32 v164, -16, v88
	v_lshl_add_u64 v[88:89], v[90:91], 0, v[164:165]
	v_lshlrev_b64 v[88:89], 12, v[88:89]
	v_lshl_add_u64 v[88:89], v[98:99], 0, v[88:89]
	global_store_dwordx4 v[88:89], v[84:87], off

; DI void epi_slab(const GemmCfg c, const f32x16 (&acc)[4], float* sW, const float* rss, const size_t row0, const int g, const int lane,
;                  float* const g_h, u16* const g_hb, float* const g_out, const int final_out) {
;     ...
;     const int c4 = l31 * 4;
;     const int col = g * 128 + c4;
;     const float sc = (K == DFF ? 0.5f : 1.f);
; #pragma unroll
;     for (int hb_ = 0; hb_ < 2; ++hb_) {
;       f32x4 hv[8];
; #pragma unroll
;       for (int i8 = 0; i8 < 8; ++i8) hv[i8] = *(const f32x4*)(g_h + (row0 + hh + 2 * (hb_ * 8 + i8)) * D + col);
; #pragma unroll
;       for (int i8 = 0; i8 < 8; ++i8) {
;         const int r = hh + 2 * (hb_ * 8 + i8);
;         const size_t row = row0 + r;
;         f32x4 v = *(const f32x4*)(sW + r * 132 + c4);
;         f32x4 o = hv[i8] + v * sc;
;         *(f32x4*)(g_h + row * D + col) = o;
;         *(u32x2*)(g_hb + row * D + col) = MK2(pack2(o[0], o[1]), pack2(o[2], o[3]));
;         if (final_out) {
;           const int b = (int)(row / T), t = (int)(row % T);
;           if (t >= 16) *(f32x4*)(g_out + ((size_t)b * 2048 + (t - 16)) * D + col) = o;
;         }
;       }
.LBB0_139:
	ds_read_b128 v[86:89], v106 offset:2112
	v_add_u32_e32 v84, 6, v128
	v_ashrrev_i32_e32 v85, 31, v84
	v_lshl_add_u64 v[84:85], s[6:7], 0, v[84:85]
	s_and_b64 vcc, exec, s[46:47]
	s_waitcnt vmcnt(13) lgkmcnt(0)
	v_pk_fma_f32 v[80:81], v[172:173], v[86:87], v[80:81]
	v_lshlrev_b64 v[86:87], 12, v[84:85]
	v_pk_fma_f32 v[82:83], v[170:171], v[88:89], v[82:83]
	v_lshl_add_u64 v[86:87], v[96:97], 0, v[86:87]
	v_lshlrev_b64 v[88:89], 11, v[84:85]
	global_store_dwordx4 v[86:87], v[80:83], off nt
	v_cvt_pk_bf16_f32 v86, v80, v81
	v_cvt_pk_bf16_f32 v87, v82, v83
	v_lshrrev_b32_e32 v142, 5, v88
	v_lshl_add_u64 v[88:89], v[100:101], 0, v[88:89]
	global_store_dwordx2 v[88:89], v[86:87], off
	v_mov_b32_e32 v141, 0
	v_dot2c_f32_bf16_e32 v141, v86, v86
	v_dot2c_f32_bf16_e32 v141, v87, v87
	s_nop 4
	v_add_f32_dpp v141, v141, v141 quad_perm:[1,0,3,2] row_mask:0xf bank_mask:0xf
	s_nop 1
	v_add_f32_dpp v141, v141, v141 quad_perm:[2,3,0,1] row_mask:0xf bank_mask:0xf
	s_nop 1
	v_add_f32_dpp v141, v141, v141 row_half_mirror row_mask:0xf bank_mask:0xf
	s_nop 1
	v_add_f32_dpp v141, v141, v141 row_mirror row_mask:0xf bank_mask:0xf
	v_lshl_add_u64 v[144:145], v[142:143], 0, v[146:147]
	global_store_dword v[144:145], v141, off
	s_cbranch_vccnz .LBB0_143
	s_mov_b32 s8, 0xe03f80ff
	v_mul_hi_u32 v164, v84, s8
	v_mad_u64_u32 v[86:87], s[14:15], v85, s8, v[164:165]
	v_mov_b32_e32 v164, v87
	v_mov_b32_e32 v87, v165
	s_mov_b32 s8, 0xfe03f80f
	v_mad_u64_u32 v[86:87], s[14:15], v84, s8, v[86:87]
	v_mov_b32_e32 v86, v87
	v_mov_b32_e32 v87, v165
	v_lshl_add_u64 v[86:87], v[164:165], 0, v[86:87]
	v_mad_u64_u32 v[86:87], s[14:15], v85, s8, v[86:87]
	v_alignbit_b32 v88, v87, v86, 11
	s_movk_i32 s8, 0x810
	v_mad_u64_u32 v[88:89], s[14:15], v88, s8, 0
	v_lshrrev_b32_e32 v90, 11, v87
	v_mad_u32_u24 v89, v90, s8, v89
	v_sub_co_u32_e32 v84, vcc, v84, v88
	s_nop 1
	v_subb_co_u32_e32 v85, vcc, v85, v89, vcc
	v_cmp_lt_u64_e32 vcc, 15, v[84:85]
	s_and_saveexec_b64 s[14:15], vcc
	s_cbranch_execz .LBB0_142
	v_lshrrev_b64 v[86:87], 11, v[86:87]
	v_mov_b32_e32 v88, v165
	v_mov_b32_e32 v89, v86
	v_ashrrev_i64 v[86:87], 21, v[88:89]
	v_add_u32_e32 v164, -16, v84
	v_lshl_add_u64 v[84:85], v[86:87], 0, v[164:165]
	v_lshlrev_b64 v[84:85], 12, v[84:85]
	v_lshl_add_u64 v[84:85], v[98:99], 0, v[84:85]
	global_store_dwordx4 v[84:85], v[80:83], off

; DI void epi_slab(const GemmCfg c, const f32x16 (&acc)[4], float* sW, const float* rss, const size_t row0, const int g, const int lane,
;                  float* const g_h, u16* const g_hb, float* const g_out, const int final_out) {
;     ...
;     const int c4 = l31 * 4;
;     const int col = g * 128 + c4;
;     const float sc = (K == DFF ? 0.5f : 1.f);
; #pragma unroll
;     for (int hb_ = 0; hb_ < 2; ++hb_) {
;       f32x4 hv[8];
; #pragma unroll
;       for (int i8 = 0; i8 < 8; ++i8) hv[i8] = *(const f32x4*)(g_h + (row0 + hh + 2 * (hb_ * 8 + i8)) * D + col);
; #pragma unroll
;       for (int i8 = 0; i8 < 8; ++i8) {
;         const int r = hh + 2 * (hb_ * 8 + i8);
;         const size_t row = row0 + r;
;         f32x4 v = *(const f32x4*)(sW + r * 132 + c4);
;         f32x4 o = hv[i8] + v * sc;
;         *(f32x4*)(g_h + row * D + col) = o;
;         *(u32x2*)(g_hb + row * D + col) = MK2(pack2(o[0], o[1]), pack2(o[2], o[3]));
;         if (final_out) {
;           const int b = (int)(row / T), t = (int)(row % T);
;           if (t >= 16) *(f32x4*)(g_out + ((size_t)b * 2048 + (t - 16)) * D + col) = o;
;         }
;       }
.LBB0_143:
	ds_read_b128 v[82:85], v106 offset:3168
	v_add_u32_e32 v80, 8, v128
	v_ashrrev_i32_e32 v81, 31, v80
	v_lshl_add_u64 v[80:81], s[6:7], 0, v[80:81]
	v_mov_b32_e32 v171, v170
	s_waitcnt vmcnt(15) lgkmcnt(0)
	v_pk_fma_f32 v[76:77], v[172:173], v[82:83], v[76:77]
	v_lshlrev_b64 v[82:83], 12, v[80:81]
	v_pk_fma_f32 v[78:79], v[170:171], v[84:85], v[78:79]
	v_lshl_add_u64 v[82:83], v[96:97], 0, v[82:83]
	v_lshlrev_b64 v[84:85], 11, v[80:81]
	global_store_dwordx4 v[82:83], v[76:79], off nt
	v_cvt_pk_bf16_f32 v82, v76, v77
	v_cvt_pk_bf16_f32 v83, v78, v79
	v_lshrrev_b32_e32 v142, 5, v84
	v_lshl_add_u64 v[84:85], v[100:101], 0, v[84:85]
	s_and_b64 vcc, exec, s[46:47]
	global_store_dwordx2 v[84:85], v[82:83], off
	v_mov_b32_e32 v141, 0
	v_dot2c_f32_bf16_e32 v141, v82, v82
	v_dot2c_f32_bf16_e32 v141, v83, v83
	s_nop 4
	v_add_f32_dpp v141, v141, v141 quad_perm:[1,0,3,2] row_mask:0xf bank_mask:0xf
	s_nop 1
	v_add_f32_dpp v141, v141, v141 quad_perm:[2,3,0,1] row_mask:0xf bank_mask:0xf
	s_nop 1
	v_add_f32_dpp v141, v141, v141 row_half_mirror row_mask:0xf bank_mask:0xf
	s_nop 1
	v_add_f32_dpp v141, v141, v141 row_mirror row_mask:0xf bank_mask:0xf
	v_lshl_add_u64 v[144:145], v[142:143], 0, v[146:147]
	global_store_dword v[144:145], v141, off
	s_cbranch_vccnz .LBB0_147
	s_mov_b32 s8, 0xe03f80ff
	v_mul_hi_u32 v164, v80, s8
	v_mad_u64_u32 v[82:83], s[14:15], v81, s8, v[164:165]
	v_mov_b32_e32 v164, v83
	v_mov_b32_e32 v83, v165
	s_mov_b32 s8, 0xfe03f80f
	v_mad_u64_u32 v[82:83], s[14:15], v80, s8, v[82:83]
	v_mov_b32_e32 v82, v83
	v_mov_b32_e32 v83, v165
	v_lshl_add_u64 v[82:83], v[164:165], 0, v[82:83]
	v_mad_u64_u32 v[82:83], s[14:15], v81, s8, v[82:83]
	v_alignbit_b32 v84, v83, v82, 11
	s_movk_i32 s8, 0x810
	v_mad_u64_u32 v[84:85], s[14:15], v84, s8, 0
	v_lshrrev_b32_e32 v86, 11, v83
	v_mad_u32_u24 v85, v86, s8, v85
	v_sub_co_u32_e32 v80, vcc, v80, v84
	s_nop 1
	v_subb_co_u32_e32 v81, vcc, v81, v85, vcc
	v_cmp_lt_u64_e32 vcc, 15, v[80:81]
	s_and_saveexec_b64 s[14:15], vcc
	s_cbranch_execz .LBB0_146
	v_lshrrev_b64 v[82:83], 11, v[82:83]
	v_mov_b32_e32 v84, v165
	v_mov_b32_e32 v85, v82
	v_ashrrev_i64 v[82:83], 21, v[84:85]
	v_add_u32_e32 v164, -16, v80
	v_lshl_add_u64 v[80:81], v[82:83], 0, v[164:165]
	v_lshlrev_b64 v[80:81], 12, v[80:81]
	v_lshl_add_u64 v[80:81], v[98:99], 0, v[80:81]
	global_store_dwordx4 v[80:81], v[76:79], off

; DI void epi_slab(const GemmCfg c, const f32x16 (&acc)[4], float* sW, const float* rss, const size_t row0, const int g, const int lane,
;                  float* const g_h, u16* const g_hb, float* const g_out, const int final_out) {
;     ...
;     const int c4 = l31 * 4;
;     const int col = g * 128 + c4;
;     const float sc = (K == DFF ? 0.5f : 1.f);
; #pragma unroll
;     for (int hb_ = 0; hb_ < 2; ++hb_) {
;       f32x4 hv[8];
; #pragma unroll
;       for (int i8 = 0; i8 < 8; ++i8) hv[i8] = *(const f32x4*)(g_h + (row0 + hh + 2 * (hb_ * 8 + i8)) * D + col);
; #pragma unroll
;       for (int i8 = 0; i8 < 8; ++i8) {
;         const int r = hh + 2 * (hb_ * 8 + i8);
;         const size_t row = row0 + r;
;         f32x4 v = *(const f32x4*)(sW + r * 132 + c4);
;         f32x4 o = hv[i8] + v * sc;
;         *(f32x4*)(g_h + row * D + col) = o;
;         *(u32x2*)(g_hb + row * D + col) = MK2(pack2(o[0], o[1]), pack2(o[2], o[3]));
;         if (final_out) {
;           const int b = (int)(row / T), t = (int)(row % T);
;           if (t >= 16) *(f32x4*)(g_out + ((size_t)b * 2048 + (t - 16)) * D + col) = o;
;         }
;       }
.LBB0_147:
	ds_read_b128 v[78:81], v106 offset:4224
	v_add_u32_e32 v76, 10, v128
	v_ashrrev_i32_e32 v77, 31, v76
	v_lshl_add_u64 v[76:77], s[6:7], 0, v[76:77]
	s_and_b64 vcc, exec, s[46:47]
	s_waitcnt vmcnt(17) lgkmcnt(0)
	v_pk_fma_f32 v[72:73], v[172:173], v[78:79], v[72:73]
	v_lshlrev_b64 v[78:79], 12, v[76:77]
	v_pk_fma_f32 v[74:75], v[170:171], v[80:81], v[74:75]
	v_lshl_add_u64 v[78:79], v[96:97], 0, v[78:79]
	v_lshlrev_b64 v[80:81], 11, v[76:77]
	global_store_dwordx4 v[78:79], v[72:75], off nt
	v_cvt_pk_bf16_f32 v78, v72, v73
	v_cvt_pk_bf16_f32 v79, v74, v75
	v_lshrrev_b32_e32 v142, 5, v80
	v_lshl_add_u64 v[80:81], v[100:101], 0, v[80:81]
	global_store_dwordx2 v[80:81], v[78:79], off
	v_mov_b32_e32 v141, 0
	v_dot2c_f32_bf16_e32 v141, v78, v78
	v_dot2c_f32_bf16_e32 v141, v79, v79
	s_nop 4
	v_add_f32_dpp v141, v141, v141 quad_perm:[1,0,3,2] row_mask:0xf bank_mask:0xf
	s_nop 1
	v_add_f32_dpp v141, v141, v141 quad_perm:[2,3,0,1] row_mask:0xf bank_mask:0xf
	s_nop 1
	v_add_f32_dpp v141, v141, v141 row_half_mirror row_mask:0xf bank_mask:0xf
	s_nop 1
	v_add_f32_dpp v141, v141, v141 row_mirror row_mask:0xf bank_mask:0xf
	v_lshl_add_u64 v[144:145], v[142:143], 0, v[146:147]
	global_store_dword v[144:145], v141, off
	s_cbranch_vccnz .LBB0_151
	s_mov_b32 s8, 0xe03f80ff
	v_mul_hi_u32 v164, v76, s8
	v_mad_u64_u32 v[78:79], s[14:15], v77, s8, v[164:165]
	v_mov_b32_e32 v164, v79
	v_mov_b32_e32 v79, v165
	s_mov_b32 s8, 0xfe03f80f
	v_mad_u64_u32 v[78:79], s[14:15], v76, s8, v[78:79]
	v_mov_b32_e32 v78, v79
	v_mov_b32_e32 v79, v165
	v_lshl_add_u64 v[78:79], v[164:165], 0, v[78:79]
	v_mad_u64_u32 v[78:79], s[14:15], v77, s8, v[78:79]
	v_alignbit_b32 v80, v79, v78, 11
	s_movk_i32 s8, 0x810
	v_mad_u64_u32 v[80:81], s[14:15], v80, s8, 0
	v_lshrrev_b32_e32 v82, 11, v79
	v_mad_u32_u24 v81, v82, s8, v81
	v_sub_co_u32_e32 v76, vcc, v76, v80
	s_nop 1
	v_subb_co_u32_e32 v77, vcc, v77, v81, vcc
	v_cmp_lt_u64_e32 vcc, 15, v[76:77]
	s_and_saveexec_b64 s[14:15], vcc
	s_cbranch_execz .LBB0_150
	v_lshrrev_b64 v[78:79], 11, v[78:79]
	v_mov_b32_e32 v80, v165
	v_mov_b32_e32 v81, v78
	v_ashrrev_i64 v[78:79], 21, v[80:81]
	v_add_u32_e32 v164, -16, v76
	v_lshl_add_u64 v[76:77], v[78:79], 0, v[164:165]
	v_lshlrev_b64 v[76:77], 12, v[76:77]
	v_lshl_add_u64 v[76:77], v[98:99], 0, v[76:77]
	global_store_dwordx4 v[76:77], v[72:75], off

; DI void epi_slab(const GemmCfg c, const f32x16 (&acc)[4], float* sW, const float* rss, const size_t row0, const int g, const int lane,
;                  float* const g_h, u16* const g_hb, float* const g_out, const int final_out) {
;     ...
;     const int c4 = l31 * 4;
;     const int col = g * 128 + c4;
;     const float sc = (K == DFF ? 0.5f : 1.f);
; #pragma unroll
;     for (int hb_ = 0; hb_ < 2; ++hb_) {
;       f32x4 hv[8];
; #pragma unroll
;       for (int i8 = 0; i8 < 8; ++i8) hv[i8] = *(const f32x4*)(g_h + (row0 + hh + 2 * (hb_ * 8 + i8)) * D + col);
; #pragma unroll
;       for (int i8 = 0; i8 < 8; ++i8) {
;         const int r = hh + 2 * (hb_ * 8 + i8);
;         const size_t row = row0 + r;
;         f32x4 v = *(const f32x4*)(sW + r * 132 + c4);
;         f32x4 o = hv[i8] + v * sc;
;         *(f32x4*)(g_h + row * D + col) = o;
;         *(u32x2*)(g_hb + row * D + col) = MK2(pack2(o[0], o[1]), pack2(o[2], o[3]));
;         if (final_out) {
;           const int b = (int)(row / T), t = (int)(row % T);
;           if (t >= 16) *(f32x4*)(g_out + ((size_t)b * 2048 + (t - 16)) * D + col) = o;
;         }
;       }
.LBB0_151:
	ds_read_b128 v[74:77], v106 offset:5280
	v_add_u32_e32 v72, 12, v128
	v_ashrrev_i32_e32 v73, 31, v72
	v_lshl_add_u64 v[72:73], s[6:7], 0, v[72:73]
	v_mov_b32_e32 v171, v170
	s_waitcnt vmcnt(19) lgkmcnt(0)
	v_pk_fma_f32 v[68:69], v[172:173], v[74:75], v[68:69]
	v_lshlrev_b64 v[74:75], 12, v[72:73]
	v_pk_fma_f32 v[70:71], v[170:171], v[76:77], v[70:71]
	v_lshl_add_u64 v[74:75], v[96:97], 0, v[74:75]
	v_lshlrev_b64 v[76:77], 11, v[72:73]
	global_store_dwordx4 v[74:75], v[68:71], off nt
	v_cvt_pk_bf16_f32 v74, v68, v69
	v_cvt_pk_bf16_f32 v75, v70, v71
	v_lshrrev_b32_e32 v142, 5, v76
	v_lshl_add_u64 v[76:77], v[100:101], 0, v[76:77]
	s_and_b64 vcc, exec, s[46:47]
	global_store_dwordx2 v[76:77], v[74:75], off
	v_mov_b32_e32 v141, 0
	v_dot2c_f32_bf16_e32 v141, v74, v74
	v_dot2c_f32_bf16_e32 v141, v75, v75
	s_nop 4
	v_add_f32_dpp v141, v141, v141 quad_perm:[1,0,3,2] row_mask:0xf bank_mask:0xf
	s_nop 1
	v_add_f32_dpp v141, v141, v141 quad_perm:[2,3,0,1] row_mask:0xf bank_mask:0xf
	s_nop 1
	v_add_f32_dpp v141, v141, v141 row_half_mirror row_mask:0xf bank_mask:0xf
	s_nop 1
	v_add_f32_dpp v141, v141, v141 row_mirror row_mask:0xf bank_mask:0xf
	v_lshl_add_u64 v[144:145], v[142:143], 0, v[146:147]
	global_store_dword v[144:145], v141, off
	s_cbranch_vccnz .LBB0_155
	s_mov_b32 s8, 0xe03f80ff
	v_mul_hi_u32 v164, v72, s8
	v_mad_u64_u32 v[74:75], s[14:15], v73, s8, v[164:165]
	v_mov_b32_e32 v164, v75
	v_mov_b32_e32 v75, v165
	s_mov_b32 s8, 0xfe03f80f
	v_mad_u64_u32 v[74:75], s[14:15], v72, s8, v[74:75]
	v_mov_b32_e32 v74, v75
	v_mov_b32_e32 v75, v165
	v_lshl_add_u64 v[74:75], v[164:165], 0, v[74:75]
	v_mad_u64_u32 v[74:75], s[14:15], v73, s8, v[74:75]
	v_alignbit_b32 v76, v75, v74, 11
	s_movk_i32 s8, 0x810
	v_mad_u64_u32 v[76:77], s[14:15], v76, s8, 0
	v_lshrrev_b32_e32 v78, 11, v75
	v_mad_u32_u24 v77, v78, s8, v77
	v_sub_co_u32_e32 v72, vcc, v72, v76
	s_nop 1
	v_subb_co_u32_e32 v73, vcc, v73, v77, vcc
	v_cmp_lt_u64_e32 vcc, 15, v[72:73]
	s_and_saveexec_b64 s[14:15], vcc
	s_cbranch_execz .LBB0_154
	v_lshrrev_b64 v[74:75], 11, v[74:75]
	v_mov_b32_e32 v76, v165
	v_mov_b32_e32 v77, v74
	v_ashrrev_i64 v[74:75], 21, v[76:77]
	v_add_u32_e32 v164, -16, v72
	v_lshl_add_u64 v[72:73], v[74:75], 0, v[164:165]
	v_lshlrev_b64 v[72:73], 12, v[72:73]
	v_lshl_add_u64 v[72:73], v[98:99], 0, v[72:73]
	global_store_dwordx4 v[72:73], v[68:71], off

; DI void epi_slab(const GemmCfg c, const f32x16 (&acc)[4], float* sW, const float* rss, const size_t row0, const int g, const int lane,
;                  float* const g_h, u16* const g_hb, float* const g_out, const int final_out) {
;     ...
;     const int c4 = l31 * 4;
;     const int col = g * 128 + c4;
;     const float sc = (K == DFF ? 0.5f : 1.f);
; #pragma unroll
;     for (int hb_ = 0; hb_ < 2; ++hb_) {
;       f32x4 hv[8];
; #pragma unroll
;       for (int i8 = 0; i8 < 8; ++i8) hv[i8] = *(const f32x4*)(g_h + (row0 + hh + 2 * (hb_ * 8 + i8)) * D + col);
; #pragma unroll
;       for (int i8 = 0; i8 < 8; ++i8) {
;         const int r = hh + 2 * (hb_ * 8 + i8);
;         const size_t row = row0 + r;
;         f32x4 v = *(const f32x4*)(sW + r * 132 + c4);
;         f32x4 o = hv[i8] + v * sc;
;         *(f32x4*)(g_h + row * D + col) = o;
;         *(u32x2*)(g_hb + row * D + col) = MK2(pack2(o[0], o[1]), pack2(o[2], o[3]));
;         if (final_out) {
;           const int b = (int)(row / T), t = (int)(row % T);
;           if (t >= 16) *(f32x4*)(g_out + ((size_t)b * 2048 + (t - 16)) * D + col) = o;
;         }
;       }
.LBB0_155:
	ds_read_b128 v[70:73], v106 offset:6336
	v_add_u32_e32 v68, 14, v128
	v_ashrrev_i32_e32 v69, 31, v68
	v_lshl_add_u64 v[68:69], s[6:7], 0, v[68:69]
	s_and_b64 vcc, exec, s[46:47]
	s_waitcnt vmcnt(21) lgkmcnt(0)
	v_pk_fma_f32 v[64:65], v[172:173], v[70:71], v[64:65]
	v_lshlrev_b64 v[70:71], 12, v[68:69]
	v_pk_fma_f32 v[66:67], v[170:171], v[72:73], v[66:67]
	v_lshl_add_u64 v[70:71], v[96:97], 0, v[70:71]
	v_lshlrev_b64 v[72:73], 11, v[68:69]
	global_store_dwordx4 v[70:71], v[64:67], off nt
	v_cvt_pk_bf16_f32 v70, v64, v65
	v_cvt_pk_bf16_f32 v71, v66, v67
	v_lshrrev_b32_e32 v142, 5, v72
	v_lshl_add_u64 v[72:73], v[100:101], 0, v[72:73]
	global_store_dwordx2 v[72:73], v[70:71], off
	v_mov_b32_e32 v141, 0
	v_dot2c_f32_bf16_e32 v141, v70, v70
	v_dot2c_f32_bf16_e32 v141, v71, v71
	s_nop 4
	v_add_f32_dpp v141, v141, v141 quad_perm:[1,0,3,2] row_mask:0xf bank_mask:0xf
	s_nop 1
	v_add_f32_dpp v141, v141, v141 quad_perm:[2,3,0,1] row_mask:0xf bank_mask:0xf
	s_nop 1
	v_add_f32_dpp v141, v141, v141 row_half_mirror row_mask:0xf bank_mask:0xf
	s_nop 1
	v_add_f32_dpp v141, v141, v141 row_mirror row_mask:0xf bank_mask:0xf
	v_lshl_add_u64 v[144:145], v[142:143], 0, v[146:147]
	global_store_dword v[144:145], v141, off
	s_cbranch_vccnz .LBB0_159
	s_mov_b32 s8, 0xe03f80ff
	v_mul_hi_u32 v164, v68, s8
	v_mad_u64_u32 v[70:71], s[14:15], v69, s8, v[164:165]
	v_mov_b32_e32 v164, v71
	v_mov_b32_e32 v71, v165
	s_mov_b32 s8, 0xfe03f80f
	v_mad_u64_u32 v[70:71], s[14:15], v68, s8, v[70:71]
	v_mov_b32_e32 v70, v71
	v_mov_b32_e32 v71, v165
	v_lshl_add_u64 v[70:71], v[164:165], 0, v[70:71]
	v_mad_u64_u32 v[70:71], s[14:15], v69, s8, v[70:71]
	v_alignbit_b32 v72, v71, v70, 11
	s_movk_i32 s8, 0x810
	v_mad_u64_u32 v[72:73], s[14:15], v72, s8, 0
	v_lshrrev_b32_e32 v74, 11, v71
	v_mad_u32_u24 v73, v74, s8, v73
	v_sub_co_u32_e32 v68, vcc, v68, v72
	s_nop 1
	v_subb_co_u32_e32 v69, vcc, v69, v73, vcc
	v_cmp_lt_u64_e32 vcc, 15, v[68:69]
	s_and_saveexec_b64 s[14:15], vcc
	s_cbranch_execz .LBB0_158
	v_lshrrev_b64 v[70:71], 11, v[70:71]
	v_mov_b32_e32 v72, v165
	v_mov_b32_e32 v73, v70
	v_ashrrev_i64 v[70:71], 21, v[72:73]
	v_add_u32_e32 v164, -16, v68
	v_lshl_add_u64 v[68:69], v[70:71], 0, v[164:165]
	v_lshlrev_b64 v[68:69], 12, v[68:69]
	v_lshl_add_u64 v[68:69], v[98:99], 0, v[68:69]
	global_store_dwordx4 v[68:69], v[64:67], off

; DI void epi_slab(const GemmCfg c, const f32x16 (&acc)[4], float* sW, const float* rss, const size_t row0, const int g, const int lane,
;                  float* const g_h, u16* const g_hb, float* const g_out, const int final_out) {
;     ...
;     const int c4 = l31 * 4;
;     const int col = g * 128 + c4;
;     const float sc = (K == DFF ? 0.5f : 1.f);
; #pragma unroll
;     for (int hb_ = 0; hb_ < 2; ++hb_) {
;       f32x4 hv[8];
; #pragma unroll
;       for (int i8 = 0; i8 < 8; ++i8) hv[i8] = *(const f32x4*)(g_h + (row0 + hh + 2 * (hb_ * 8 + i8)) * D + col);
; #pragma unroll
;       for (int i8 = 0; i8 < 8; ++i8) {
;         const int r = hh + 2 * (hb_ * 8 + i8);
;         const size_t row = row0 + r;
;         f32x4 v = *(const f32x4*)(sW + r * 132 + c4);
;         f32x4 o = hv[i8] + v * sc;
;         *(f32x4*)(g_h + row * D + col) = o;
;         *(u32x2*)(g_hb + row * D + col) = MK2(pack2(o[0], o[1]), pack2(o[2], o[3]));
;         if (final_out) {
;           const int b = (int)(row / T), t = (int)(row % T);
;           if (t >= 16) *(f32x4*)(g_out + ((size_t)b * 2048 + (t - 16)) * D + col) = o;
;         }
;       }
.LBB0_159:
	s_nop 0
	v_add_co_u32_e32 v64, vcc, 0x10000, v102
	ds_read_b128 v[108:111], v106 offset:7392
	s_nop 0
	v_addc_co_u32_e32 v65, vcc, 0, v103, vcc
	global_load_dwordx4 v[92:95], v[64:65], off
	v_add_co_u32_e32 v64, vcc, 0x12000, v102
	v_mov_b32_e32 v171, v170
	s_nop 0
	v_addc_co_u32_e32 v65, vcc, 0, v103, vcc
	global_load_dwordx4 v[88:91], v[64:65], off
	v_add_co_u32_e32 v64, vcc, 0x14000, v102
	s_waitcnt vmcnt(1) lgkmcnt(0)
	v_pk_fma_f32 v[94:95], v[170:171], v[110:111], v[94:95]
	v_addc_co_u32_e32 v65, vcc, 0, v103, vcc
	global_load_dwordx4 v[84:87], v[64:65], off
	v_add_co_u32_e32 v64, vcc, 0x16000, v102
	v_pk_fma_f32 v[92:93], v[172:173], v[108:109], v[92:93]
	s_nop 0
	v_addc_co_u32_e32 v65, vcc, 0, v103, vcc
	global_load_dwordx4 v[80:83], v[64:65], off
	v_add_co_u32_e32 v64, vcc, 0x18000, v102
	s_nop 1
	v_addc_co_u32_e32 v65, vcc, 0, v103, vcc
	global_load_dwordx4 v[76:79], v[64:65], off
	v_add_co_u32_e32 v64, vcc, 0x1a000, v102
	s_nop 1
	v_addc_co_u32_e32 v65, vcc, 0, v103, vcc
	global_load_dwordx4 v[72:75], v[64:65], off
	v_add_co_u32_e32 v64, vcc, 0x1c000, v102
	s_nop 1
	v_addc_co_u32_e32 v65, vcc, 0, v103, vcc
	global_load_dwordx4 v[68:71], v[64:65], off
	v_add_co_u32_e32 v64, vcc, 0x1e000, v102
	v_add_u32_e32 v102, 16, v128
	s_nop 0
	v_addc_co_u32_e32 v65, vcc, 0, v103, vcc
	global_load_dwordx4 v[64:67], v[64:65], off
	v_ashrrev_i32_e32 v103, 31, v102
	v_lshl_add_u64 v[102:103], s[6:7], 0, v[102:103]
	v_lshlrev_b64 v[104:105], 12, v[102:103]
	v_lshl_add_u64 v[104:105], v[96:97], 0, v[104:105]
	v_lshlrev_b64 v[108:109], 11, v[102:103]
	global_store_dwordx4 v[104:105], v[92:95], off nt
	v_cvt_pk_bf16_f32 v104, v92, v93
	v_cvt_pk_bf16_f32 v105, v94, v95
	v_lshrrev_b32_e32 v142, 5, v108
	v_lshl_add_u64 v[108:109], v[100:101], 0, v[108:109]
	s_and_b64 vcc, exec, s[46:47]
	global_store_dwordx2 v[108:109], v[104:105], off
	v_mov_b32_e32 v141, 0
	v_dot2c_f32_bf16_e32 v141, v104, v104
	v_dot2c_f32_bf16_e32 v141, v105, v105
	s_nop 4
	v_add_f32_dpp v141, v141, v141 quad_perm:[1,0,3,2] row_mask:0xf bank_mask:0xf
	s_nop 1
	v_add_f32_dpp v141, v141, v141 quad_perm:[2,3,0,1] row_mask:0xf bank_mask:0xf
	s_nop 1
	v_add_f32_dpp v141, v141, v141 row_half_mirror row_mask:0xf bank_mask:0xf
	s_nop 1
	v_add_f32_dpp v141, v141, v141 row_mirror row_mask:0xf bank_mask:0xf
	v_lshl_add_u64 v[144:145], v[142:143], 0, v[146:147]
	global_store_dword v[144:145], v141, off
	s_cbranch_vccnz .LBB0_163
	s_mov_b32 s8, 0xe03f80ff
	v_mul_hi_u32 v164, v102, s8
	v_mad_u64_u32 v[104:105], s[14:15], v103, s8, v[164:165]
	v_mov_b32_e32 v164, v105
	v_mov_b32_e32 v105, v165
	s_mov_b32 s8, 0xfe03f80f
	v_mad_u64_u32 v[104:105], s[14:15], v102, s8, v[104:105]
	v_mov_b32_e32 v104, v105
	v_mov_b32_e32 v105, v165
	v_lshl_add_u64 v[104:105], v[164:165], 0, v[104:105]
	v_mad_u64_u32 v[104:105], s[14:15], v103, s8, v[104:105]
	v_alignbit_b32 v107, v105, v104, 11
	s_movk_i32 s8, 0x810
	v_mad_u64_u32 v[108:109], s[14:15], v107, s8, 0
	v_lshrrev_b32_e32 v107, 11, v105
	v_mad_u32_u24 v107, v107, s8, v109
	v_sub_co_u32_e32 v102, vcc, v102, v108
	s_nop 1
	v_subb_co_u32_e32 v103, vcc, v103, v107, vcc
	v_cmp_lt_u64_e32 vcc, 15, v[102:103]
	s_and_saveexec_b64 s[14:15], vcc
	s_cbranch_execz .LBB0_162
	v_lshrrev_b64 v[104:105], 11, v[104:105]
	v_mov_b32_e32 v108, v165
	v_mov_b32_e32 v109, v104
	v_ashrrev_i64 v[104:105], 21, v[108:109]
	v_add_u32_e32 v164, -16, v102
	v_lshl_add_u64 v[102:103], v[104:105], 0, v[164:165]
	v_lshlrev_b64 v[102:103], 12, v[102:103]
	v_lshl_add_u64 v[102:103], v[98:99], 0, v[102:103]
	global_store_dwordx4 v[102:103], v[92:95], off

; DI void epi_slab(const GemmCfg c, const f32x16 (&acc)[4], float* sW, const float* rss, const size_t row0, const int g, const int lane,
;                  float* const g_h, u16* const g_hb, float* const g_out, const int final_out) {
;     ...
;     const int c4 = l31 * 4;
;     const int col = g * 128 + c4;
;     const float sc = (K == DFF ? 0.5f : 1.f);
; #pragma unroll
;     for (int hb_ = 0; hb_ < 2; ++hb_) {
;       f32x4 hv[8];
; #pragma unroll
;       for (int i8 = 0; i8 < 8; ++i8) hv[i8] = *(const f32x4*)(g_h + (row0 + hh + 2 * (hb_ * 8 + i8)) * D + col);
; #pragma unroll
;       for (int i8 = 0; i8 < 8; ++i8) {
;         const int r = hh + 2 * (hb_ * 8 + i8);
;         const size_t row = row0 + r;
;         f32x4 v = *(const f32x4*)(sW + r * 132 + c4);
;         f32x4 o = hv[i8] + v * sc;
;         *(f32x4*)(g_h + row * D + col) = o;
;         *(u32x2*)(g_hb + row * D + col) = MK2(pack2(o[0], o[1]), pack2(o[2], o[3]));
;         if (final_out) {
;           const int b = (int)(row / T), t = (int)(row % T);
;           if (t >= 16) *(f32x4*)(g_out + ((size_t)b * 2048 + (t - 16)) * D + col) = o;
;         }
;       }
.LBB0_163:
	ds_read_b128 v[102:105], v106 offset:8448
	v_add_u32_e32 v92, 18, v128
	v_ashrrev_i32_e32 v93, 31, v92
	v_lshl_add_u64 v[92:93], s[6:7], 0, v[92:93]
	v_lshlrev_b64 v[94:95], 12, v[92:93]
	s_waitcnt vmcnt(9) lgkmcnt(0)
	v_pk_fma_f32 v[90:91], v[170:171], v[104:105], v[90:91]
	v_pk_fma_f32 v[88:89], v[172:173], v[102:103], v[88:89]
	v_lshl_add_u64 v[94:95], v[96:97], 0, v[94:95]
	v_lshlrev_b64 v[102:103], 11, v[92:93]
	global_store_dwordx4 v[94:95], v[88:91], off nt
	v_cvt_pk_bf16_f32 v94, v88, v89
	v_cvt_pk_bf16_f32 v95, v90, v91
	v_lshrrev_b32_e32 v142, 5, v102
	v_lshl_add_u64 v[102:103], v[100:101], 0, v[102:103]
	s_and_b64 vcc, exec, s[46:47]
	global_store_dwordx2 v[102:103], v[94:95], off
	v_mov_b32_e32 v141, 0
	v_dot2c_f32_bf16_e32 v141, v94, v94
	v_dot2c_f32_bf16_e32 v141, v95, v95
	s_nop 4
	v_add_f32_dpp v141, v141, v141 quad_perm:[1,0,3,2] row_mask:0xf bank_mask:0xf
	s_nop 1
	v_add_f32_dpp v141, v141, v141 quad_perm:[2,3,0,1] row_mask:0xf bank_mask:0xf
	s_nop 1
	v_add_f32_dpp v141, v141, v141 row_half_mirror row_mask:0xf bank_mask:0xf
	s_nop 1
	v_add_f32_dpp v141, v141, v141 row_mirror row_mask:0xf bank_mask:0xf
	v_lshl_add_u64 v[144:145], v[142:143], 0, v[146:147]
	global_store_dword v[144:145], v141, off
	s_cbranch_vccnz .LBB0_167
	s_mov_b32 s8, 0xe03f80ff
	v_mul_hi_u32 v164, v92, s8
	v_mad_u64_u32 v[94:95], s[14:15], v93, s8, v[164:165]
	v_mov_b32_e32 v164, v95
	v_mov_b32_e32 v95, v165
	s_mov_b32 s8, 0xfe03f80f
	v_mad_u64_u32 v[94:95], s[14:15], v92, s8, v[94:95]
	v_mov_b32_e32 v94, v95
	v_mov_b32_e32 v95, v165
	v_lshl_add_u64 v[94:95], v[164:165], 0, v[94:95]
	v_mad_u64_u32 v[94:95], s[14:15], v93, s8, v[94:95]
	v_alignbit_b32 v102, v95, v94, 11
	s_movk_i32 s8, 0x810
	v_mad_u64_u32 v[102:103], s[14:15], v102, s8, 0
	v_lshrrev_b32_e32 v104, 11, v95
	v_mad_u32_u24 v103, v104, s8, v103
	v_sub_co_u32_e32 v92, vcc, v92, v102
	s_nop 1
	v_subb_co_u32_e32 v93, vcc, v93, v103, vcc
	v_cmp_lt_u64_e32 vcc, 15, v[92:93]
	s_and_saveexec_b64 s[14:15], vcc
	s_cbranch_execz .LBB0_166
	v_lshrrev_b64 v[94:95], 11, v[94:95]
	v_mov_b32_e32 v102, v165
	v_mov_b32_e32 v103, v94
	v_ashrrev_i64 v[94:95], 21, v[102:103]
	v_add_u32_e32 v164, -16, v92
	v_lshl_add_u64 v[92:93], v[94:95], 0, v[164:165]
	v_lshlrev_b64 v[92:93], 12, v[92:93]
	v_lshl_add_u64 v[92:93], v[98:99], 0, v[92:93]
	global_store_dwordx4 v[92:93], v[88:91], off

; DI void epi_slab(const GemmCfg c, const f32x16 (&acc)[4], float* sW, const float* rss, const size_t row0, const int g, const int lane,
;                  float* const g_h, u16* const g_hb, float* const g_out, const int final_out) {
;     ...
;     const int c4 = l31 * 4;
;     const int col = g * 128 + c4;
;     const float sc = (K == DFF ? 0.5f : 1.f);
; #pragma unroll
;     for (int hb_ = 0; hb_ < 2; ++hb_) {
;       f32x4 hv[8];
; #pragma unroll
;       for (int i8 = 0; i8 < 8; ++i8) hv[i8] = *(const f32x4*)(g_h + (row0 + hh + 2 * (hb_ * 8 + i8)) * D + col);
; #pragma unroll
;       for (int i8 = 0; i8 < 8; ++i8) {
;         const int r = hh + 2 * (hb_ * 8 + i8);
;         const size_t row = row0 + r;
;         f32x4 v = *(const f32x4*)(sW + r * 132 + c4);
;         f32x4 o = hv[i8] + v * sc;
;         *(f32x4*)(g_h + row * D + col) = o;
;         *(u32x2*)(g_hb + row * D + col) = MK2(pack2(o[0], o[1]), pack2(o[2], o[3]));
;         if (final_out) {
;           const int b = (int)(row / T), t = (int)(row % T);
;           if (t >= 16) *(f32x4*)(g_out + ((size_t)b * 2048 + (t - 16)) * D + col) = o;
;         }
;       }
.LBB0_167:
	ds_read_b128 v[90:93], v106 offset:9504
	v_add_u32_e32 v88, 20, v128
	v_ashrrev_i32_e32 v89, 31, v88
	v_lshl_add_u64 v[88:89], s[6:7], 0, v[88:89]
	v_mov_b32_e32 v171, v170
	s_waitcnt vmcnt(11) lgkmcnt(0)
	v_pk_fma_f32 v[84:85], v[172:173], v[90:91], v[84:85]
	v_lshlrev_b64 v[90:91], 12, v[88:89]
	v_pk_fma_f32 v[86:87], v[170:171], v[92:93], v[86:87]
	v_lshl_add_u64 v[90:91], v[96:97], 0, v[90:91]
	v_lshlrev_b64 v[92:93], 11, v[88:89]
	global_store_dwordx4 v[90:91], v[84:87], off nt
	v_cvt_pk_bf16_f32 v90, v84, v85
	v_cvt_pk_bf16_f32 v91, v86, v87
	v_lshrrev_b32_e32 v142, 5, v92
	v_lshl_add_u64 v[92:93], v[100:101], 0, v[92:93]
	s_and_b64 vcc, exec, s[46:47]
	global_store_dwordx2 v[92:93], v[90:91], off
	v_mov_b32_e32 v141, 0
	v_dot2c_f32_bf16_e32 v141, v90, v90
	v_dot2c_f32_bf16_e32 v141, v91, v91
	s_nop 4
	v_add_f32_dpp v141, v141, v141 quad_perm:[1,0,3,2] row_mask:0xf bank_mask:0xf
	s_nop 1
	v_add_f32_dpp v141, v141, v141 quad_perm:[2,3,0,1] row_mask:0xf bank_mask:0xf
	s_nop 1
	v_add_f32_dpp v141, v141, v141 row_half_mirror row_mask:0xf bank_mask:0xf
	s_nop 1
	v_add_f32_dpp v141, v141, v141 row_mirror row_mask:0xf bank_mask:0xf
	v_lshl_add_u64 v[144:145], v[142:143], 0, v[146:147]
	global_store_dword v[144:145], v141, off
	s_cbranch_vccnz .LBB0_171
	s_mov_b32 s8, 0xe03f80ff
	v_mul_hi_u32 v164, v88, s8
	v_mad_u64_u32 v[90:91], s[14:15], v89, s8, v[164:165]
	v_mov_b32_e32 v164, v91
	v_mov_b32_e32 v91, v165
	s_mov_b32 s8, 0xfe03f80f
	v_mad_u64_u32 v[90:91], s[14:15], v88, s8, v[90:91]
	v_mov_b32_e32 v90, v91
	v_mov_b32_e32 v91, v165
	v_lshl_add_u64 v[90:91], v[164:165], 0, v[90:91]
	v_mad_u64_u32 v[90:91], s[14:15], v89, s8, v[90:91]
	v_alignbit_b32 v92, v91, v90, 11
	s_movk_i32 s8, 0x810
	v_mad_u64_u32 v[92:93], s[14:15], v92, s8, 0
	v_lshrrev_b32_e32 v94, 11, v91
	v_mad_u32_u24 v93, v94, s8, v93
	v_sub_co_u32_e32 v88, vcc, v88, v92
	s_nop 1
	v_subb_co_u32_e32 v89, vcc, v89, v93, vcc
	v_cmp_lt_u64_e32 vcc, 15, v[88:89]
	s_and_saveexec_b64 s[14:15], vcc
	s_cbranch_execz .LBB0_170
	v_lshrrev_b64 v[90:91], 11, v[90:91]
	v_mov_b32_e32 v92, v165
	v_mov_b32_e32 v93, v90
	v_ashrrev_i64 v[90:91], 21, v[92:93]
	v_add_u32_e32 v164, -16, v88
	v_lshl_add_u64 v[88:89], v[90:91], 0, v[164:165]
	v_lshlrev_b64 v[88:89], 12, v[88:89]
	v_lshl_add_u64 v[88:89], v[98:99], 0, v[88:89]
	global_store_dwordx4 v[88:89], v[84:87], off

; DI void epi_slab(const GemmCfg c, const f32x16 (&acc)[4], float* sW, const float* rss, const size_t row0, const int g, const int lane,
;                  float* const g_h, u16* const g_hb, float* const g_out, const int final_out) {
;     ...
;     const int c4 = l31 * 4;
;     const int col = g * 128 + c4;
;     const float sc = (K == DFF ? 0.5f : 1.f);
; #pragma unroll
;     for (int hb_ = 0; hb_ < 2; ++hb_) {
;       f32x4 hv[8];
; #pragma unroll
;       for (int i8 = 0; i8 < 8; ++i8) hv[i8] = *(const f32x4*)(g_h + (row0 + hh + 2 * (hb_ * 8 + i8)) * D + col);
; #pragma unroll
;       for (int i8 = 0; i8 < 8; ++i8) {
;         const int r = hh + 2 * (hb_ * 8 + i8);
;         const size_t row = row0 + r;
;         f32x4 v = *(const f32x4*)(sW + r * 132 + c4);
;         f32x4 o = hv[i8] + v * sc;
;         *(f32x4*)(g_h + row * D + col) = o;
;         *(u32x2*)(g_hb + row * D + col) = MK2(pack2(o[0], o[1]), pack2(o[2], o[3]));
;         if (final_out) {
;           const int b = (int)(row / T), t = (int)(row % T);
;           if (t >= 16) *(f32x4*)(g_out + ((size_t)b * 2048 + (t - 16)) * D + col) = o;
;         }
;       }
.LBB0_171:
	ds_read_b128 v[86:89], v106 offset:10560
	v_add_u32_e32 v84, 22, v128
	v_ashrrev_i32_e32 v85, 31, v84
	v_lshl_add_u64 v[84:85], s[6:7], 0, v[84:85]
	s_and_b64 vcc, exec, s[46:47]
	s_waitcnt vmcnt(13) lgkmcnt(0)
	v_pk_fma_f32 v[80:81], v[172:173], v[86:87], v[80:81]
	v_lshlrev_b64 v[86:87], 12, v[84:85]
	v_pk_fma_f32 v[82:83], v[170:171], v[88:89], v[82:83]
	v_lshl_add_u64 v[86:87], v[96:97], 0, v[86:87]
	v_lshlrev_b64 v[88:89], 11, v[84:85]
	global_store_dwordx4 v[86:87], v[80:83], off nt
	v_cvt_pk_bf16_f32 v86, v80, v81
	v_cvt_pk_bf16_f32 v87, v82, v83
	v_lshrrev_b32_e32 v142, 5, v88
	v_lshl_add_u64 v[88:89], v[100:101], 0, v[88:89]
	global_store_dwordx2 v[88:89], v[86:87], off
	v_mov_b32_e32 v141, 0
	v_dot2c_f32_bf16_e32 v141, v86, v86
	v_dot2c_f32_bf16_e32 v141, v87, v87
	s_nop 4
	v_add_f32_dpp v141, v141, v141 quad_perm:[1,0,3,2] row_mask:0xf bank_mask:0xf
	s_nop 1
	v_add_f32_dpp v141, v141, v141 quad_perm:[2,3,0,1] row_mask:0xf bank_mask:0xf
	s_nop 1
	v_add_f32_dpp v141, v141, v141 row_half_mirror row_mask:0xf bank_mask:0xf
	s_nop 1
	v_add_f32_dpp v141, v141, v141 row_mirror row_mask:0xf bank_mask:0xf
	v_lshl_add_u64 v[144:145], v[142:143], 0, v[146:147]
	global_store_dword v[144:145], v141, off
	s_cbranch_vccnz .LBB0_175
	s_mov_b32 s8, 0xe03f80ff
	v_mul_hi_u32 v164, v84, s8
	v_mad_u64_u32 v[86:87], s[14:15], v85, s8, v[164:165]
	v_mov_b32_e32 v164, v87
	v_mov_b32_e32 v87, v165
	s_mov_b32 s8, 0xfe03f80f
	v_mad_u64_u32 v[86:87], s[14:15], v84, s8, v[86:87]
	v_mov_b32_e32 v86, v87
	v_mov_b32_e32 v87, v165
	v_lshl_add_u64 v[86:87], v[164:165], 0, v[86:87]
	v_mad_u64_u32 v[86:87], s[14:15], v85, s8, v[86:87]
	v_alignbit_b32 v88, v87, v86, 11
	s_movk_i32 s8, 0x810
	v_mad_u64_u32 v[88:89], s[14:15], v88, s8, 0
	v_lshrrev_b32_e32 v90, 11, v87
	v_mad_u32_u24 v89, v90, s8, v89
	v_sub_co_u32_e32 v84, vcc, v84, v88
	s_nop 1
	v_subb_co_u32_e32 v85, vcc, v85, v89, vcc
	v_cmp_lt_u64_e32 vcc, 15, v[84:85]
	s_and_saveexec_b64 s[14:15], vcc
	s_cbranch_execz .LBB0_174
	v_lshrrev_b64 v[86:87], 11, v[86:87]
	v_mov_b32_e32 v88, v165
	v_mov_b32_e32 v89, v86
	v_ashrrev_i64 v[86:87], 21, v[88:89]
	v_add_u32_e32 v164, -16, v84
	v_lshl_add_u64 v[84:85], v[86:87], 0, v[164:165]
	v_lshlrev_b64 v[84:85], 12, v[84:85]
	v_lshl_add_u64 v[84:85], v[98:99], 0, v[84:85]
	global_store_dwordx4 v[84:85], v[80:83], off

; DI void epi_slab(const GemmCfg c, const f32x16 (&acc)[4], float* sW, const float* rss, const size_t row0, const int g, const int lane,
;                  float* const g_h, u16* const g_hb, float* const g_out, const int final_out) {
;     ...
;     const int c4 = l31 * 4;
;     const int col = g * 128 + c4;
;     const float sc = (K == DFF ? 0.5f : 1.f);
; #pragma unroll
;     for (int hb_ = 0; hb_ < 2; ++hb_) {
;       f32x4 hv[8];
; #pragma unroll
;       for (int i8 = 0; i8 < 8; ++i8) hv[i8] = *(const f32x4*)(g_h + (row0 + hh + 2 * (hb_ * 8 + i8)) * D + col);
; #pragma unroll
;       for (int i8 = 0; i8 < 8; ++i8) {
;         const int r = hh + 2 * (hb_ * 8 + i8);
;         const size_t row = row0 + r;
;         f32x4 v = *(const f32x4*)(sW + r * 132 + c4);
;         f32x4 o = hv[i8] + v * sc;
;         *(f32x4*)(g_h + row * D + col) = o;
;         *(u32x2*)(g_hb + row * D + col) = MK2(pack2(o[0], o[1]), pack2(o[2], o[3]));
;         if (final_out) {
;           const int b = (int)(row / T), t = (int)(row % T);
;           if (t >= 16) *(f32x4*)(g_out + ((size_t)b * 2048 + (t - 16)) * D + col) = o;
;         }
;       }
.LBB0_175:
	ds_read_b128 v[82:85], v106 offset:11616
	v_add_u32_e32 v80, 24, v128
	v_ashrrev_i32_e32 v81, 31, v80
	v_lshl_add_u64 v[80:81], s[6:7], 0, v[80:81]
	v_mov_b32_e32 v171, v170
	s_waitcnt vmcnt(15) lgkmcnt(0)
	v_pk_fma_f32 v[76:77], v[172:173], v[82:83], v[76:77]
	v_lshlrev_b64 v[82:83], 12, v[80:81]
	v_pk_fma_f32 v[78:79], v[170:171], v[84:85], v[78:79]
	v_lshl_add_u64 v[82:83], v[96:97], 0, v[82:83]
	v_lshlrev_b64 v[84:85], 11, v[80:81]
	global_store_dwordx4 v[82:83], v[76:79], off nt
	v_cvt_pk_bf16_f32 v82, v76, v77
	v_cvt_pk_bf16_f32 v83, v78, v79
	v_lshrrev_b32_e32 v142, 5, v84
	v_lshl_add_u64 v[84:85], v[100:101], 0, v[84:85]
	s_and_b64 vcc, exec, s[46:47]
	global_store_dwordx2 v[84:85], v[82:83], off
	v_mov_b32_e32 v141, 0
	v_dot2c_f32_bf16_e32 v141, v82, v82
	v_dot2c_f32_bf16_e32 v141, v83, v83
	s_nop 4
	v_add_f32_dpp v141, v141, v141 quad_perm:[1,0,3,2] row_mask:0xf bank_mask:0xf
	s_nop 1
	v_add_f32_dpp v141, v141, v141 quad_perm:[2,3,0,1] row_mask:0xf bank_mask:0xf
	s_nop 1
	v_add_f32_dpp v141, v141, v141 row_half_mirror row_mask:0xf bank_mask:0xf
	s_nop 1
	v_add_f32_dpp v141, v141, v141 row_mirror row_mask:0xf bank_mask:0xf
	v_lshl_add_u64 v[144:145], v[142:143], 0, v[146:147]
	global_store_dword v[144:145], v141, off
	s_cbranch_vccnz .LBB0_179
	s_mov_b32 s8, 0xe03f80ff
	v_mul_hi_u32 v164, v80, s8
	v_mad_u64_u32 v[82:83], s[14:15], v81, s8, v[164:165]
	v_mov_b32_e32 v164, v83
	v_mov_b32_e32 v83, v165
	s_mov_b32 s8, 0xfe03f80f
	v_mad_u64_u32 v[82:83], s[14:15], v80, s8, v[82:83]
	v_mov_b32_e32 v82, v83
	v_mov_b32_e32 v83, v165
	v_lshl_add_u64 v[82:83], v[164:165], 0, v[82:83]
	v_mad_u64_u32 v[82:83], s[14:15], v81, s8, v[82:83]
	v_alignbit_b32 v84, v83, v82, 11
	s_movk_i32 s8, 0x810
	v_mad_u64_u32 v[84:85], s[14:15], v84, s8, 0
	v_lshrrev_b32_e32 v86, 11, v83
	v_mad_u32_u24 v85, v86, s8, v85
	v_sub_co_u32_e32 v80, vcc, v80, v84
	s_nop 1
	v_subb_co_u32_e32 v81, vcc, v81, v85, vcc
	v_cmp_lt_u64_e32 vcc, 15, v[80:81]
	s_and_saveexec_b64 s[14:15], vcc
	s_cbranch_execz .LBB0_178
	v_lshrrev_b64 v[82:83], 11, v[82:83]
	v_mov_b32_e32 v84, v165
	v_mov_b32_e32 v85, v82
	v_ashrrev_i64 v[82:83], 21, v[84:85]
	v_add_u32_e32 v164, -16, v80
	v_lshl_add_u64 v[80:81], v[82:83], 0, v[164:165]
	v_lshlrev_b64 v[80:81], 12, v[80:81]
	v_lshl_add_u64 v[80:81], v[98:99], 0, v[80:81]
	global_store_dwordx4 v[80:81], v[76:79], off

; DI void epi_slab(const GemmCfg c, const f32x16 (&acc)[4], float* sW, const float* rss, const size_t row0, const int g, const int lane,
;                  float* const g_h, u16* const g_hb, float* const g_out, const int final_out) {
;     ...
;     const int c4 = l31 * 4;
;     const int col = g * 128 + c4;
;     const float sc = (K == DFF ? 0.5f : 1.f);
; #pragma unroll
;     for (int hb_ = 0; hb_ < 2; ++hb_) {
;       f32x4 hv[8];
; #pragma unroll
;       for (int i8 = 0; i8 < 8; ++i8) hv[i8] = *(const f32x4*)(g_h + (row0 + hh + 2 * (hb_ * 8 + i8)) * D + col);
; #pragma unroll
;       for (int i8 = 0; i8 < 8; ++i8) {
;         const int r = hh + 2 * (hb_ * 8 + i8);
;         const size_t row = row0 + r;
;         f32x4 v = *(const f32x4*)(sW + r * 132 + c4);
;         f32x4 o = hv[i8] + v * sc;
;         *(f32x4*)(g_h + row * D + col) = o;
;         *(u32x2*)(g_hb + row * D + col) = MK2(pack2(o[0], o[1]), pack2(o[2], o[3]));
;         if (final_out) {
;           const int b = (int)(row / T), t = (int)(row % T);
;           if (t >= 16) *(f32x4*)(g_out + ((size_t)b * 2048 + (t - 16)) * D + col) = o;
;         }
;       }
.LBB0_179:
	ds_read_b128 v[78:81], v106 offset:12672
	v_add_u32_e32 v76, 26, v128
	v_ashrrev_i32_e32 v77, 31, v76
	v_lshl_add_u64 v[76:77], s[6:7], 0, v[76:77]
	s_and_b64 vcc, exec, s[46:47]
	s_waitcnt vmcnt(17) lgkmcnt(0)
	v_pk_fma_f32 v[72:73], v[172:173], v[78:79], v[72:73]
	v_lshlrev_b64 v[78:79], 12, v[76:77]
	v_pk_fma_f32 v[74:75], v[170:171], v[80:81], v[74:75]
	v_lshl_add_u64 v[78:79], v[96:97], 0, v[78:79]
	v_lshlrev_b64 v[80:81], 11, v[76:77]
	global_store_dwordx4 v[78:79], v[72:75], off nt
	v_cvt_pk_bf16_f32 v78, v72, v73
	v_cvt_pk_bf16_f32 v79, v74, v75
	v_lshrrev_b32_e32 v142, 5, v80
	v_lshl_add_u64 v[80:81], v[100:101], 0, v[80:81]
	global_store_dwordx2 v[80:81], v[78:79], off
	v_mov_b32_e32 v141, 0
	v_dot2c_f32_bf16_e32 v141, v78, v78
	v_dot2c_f32_bf16_e32 v141, v79, v79
	s_nop 4
	v_add_f32_dpp v141, v141, v141 quad_perm:[1,0,3,2] row_mask:0xf bank_mask:0xf
	s_nop 1
	v_add_f32_dpp v141, v141, v141 quad_perm:[2,3,0,1] row_mask:0xf bank_mask:0xf
	s_nop 1
	v_add_f32_dpp v141, v141, v141 row_half_mirror row_mask:0xf bank_mask:0xf
	s_nop 1
	v_add_f32_dpp v141, v141, v141 row_mirror row_mask:0xf bank_mask:0xf
	v_lshl_add_u64 v[144:145], v[142:143], 0, v[146:147]
	global_store_dword v[144:145], v141, off
	s_cbranch_vccnz .LBB0_183
	s_mov_b32 s8, 0xe03f80ff
	v_mul_hi_u32 v164, v76, s8
	v_mad_u64_u32 v[78:79], s[14:15], v77, s8, v[164:165]
	v_mov_b32_e32 v164, v79
	v_mov_b32_e32 v79, v165
	s_mov_b32 s8, 0xfe03f80f
	v_mad_u64_u32 v[78:79], s[14:15], v76, s8, v[78:79]
	v_mov_b32_e32 v78, v79
	v_mov_b32_e32 v79, v165
	v_lshl_add_u64 v[78:79], v[164:165], 0, v[78:79]
	v_mad_u64_u32 v[78:79], s[14:15], v77, s8, v[78:79]
	v_alignbit_b32 v80, v79, v78, 11
	s_movk_i32 s8, 0x810
	v_mad_u64_u32 v[80:81], s[14:15], v80, s8, 0
	v_lshrrev_b32_e32 v82, 11, v79
	v_mad_u32_u24 v81, v82, s8, v81
	v_sub_co_u32_e32 v76, vcc, v76, v80
	s_nop 1
	v_subb_co_u32_e32 v77, vcc, v77, v81, vcc
	v_cmp_lt_u64_e32 vcc, 15, v[76:77]
	s_and_saveexec_b64 s[14:15], vcc
	s_cbranch_execz .LBB0_182
	v_lshrrev_b64 v[78:79], 11, v[78:79]
	v_mov_b32_e32 v80, v165
	v_mov_b32_e32 v81, v78
	v_ashrrev_i64 v[78:79], 21, v[80:81]
	v_add_u32_e32 v164, -16, v76
	v_lshl_add_u64 v[76:77], v[78:79], 0, v[164:165]
	v_lshlrev_b64 v[76:77], 12, v[76:77]
	v_lshl_add_u64 v[76:77], v[98:99], 0, v[76:77]
	global_store_dwordx4 v[76:77], v[72:75], off

; DI void epi_slab(const GemmCfg c, const f32x16 (&acc)[4], float* sW, const float* rss, const size_t row0, const int g, const int lane,
;                  float* const g_h, u16* const g_hb, float* const g_out, const int final_out) {
;     ...
;     const int c4 = l31 * 4;
;     const int col = g * 128 + c4;
;     const float sc = (K == DFF ? 0.5f : 1.f);
; #pragma unroll
;     for (int hb_ = 0; hb_ < 2; ++hb_) {
;       f32x4 hv[8];
; #pragma unroll
;       for (int i8 = 0; i8 < 8; ++i8) hv[i8] = *(const f32x4*)(g_h + (row0 + hh + 2 * (hb_ * 8 + i8)) * D + col);
; #pragma unroll
;       for (int i8 = 0; i8 < 8; ++i8) {
;         const int r = hh + 2 * (hb_ * 8 + i8);
;         const size_t row = row0 + r;
;         f32x4 v = *(const f32x4*)(sW + r * 132 + c4);
;         f32x4 o = hv[i8] + v * sc;
;         *(f32x4*)(g_h + row * D + col) = o;
;         *(u32x2*)(g_hb + row * D + col) = MK2(pack2(o[0], o[1]), pack2(o[2], o[3]));
;         if (final_out) {
;           const int b = (int)(row / T), t = (int)(row % T);
;           if (t >= 16) *(f32x4*)(g_out + ((size_t)b * 2048 + (t - 16)) * D + col) = o;
;         }
;       }
.LBB0_183:
	ds_read_b128 v[74:77], v106 offset:13728
	v_add_u32_e32 v72, 28, v128
	v_ashrrev_i32_e32 v73, 31, v72
	v_lshl_add_u64 v[72:73], s[6:7], 0, v[72:73]
	v_mov_b32_e32 v171, v170
	s_waitcnt vmcnt(19) lgkmcnt(0)
	v_pk_fma_f32 v[68:69], v[172:173], v[74:75], v[68:69]
	v_lshlrev_b64 v[74:75], 12, v[72:73]
	v_pk_fma_f32 v[70:71], v[170:171], v[76:77], v[70:71]
	v_lshl_add_u64 v[74:75], v[96:97], 0, v[74:75]
	v_lshlrev_b64 v[76:77], 11, v[72:73]
	global_store_dwordx4 v[74:75], v[68:71], off nt
	v_cvt_pk_bf16_f32 v74, v68, v69
	v_cvt_pk_bf16_f32 v75, v70, v71
	v_lshrrev_b32_e32 v142, 5, v76
	v_lshl_add_u64 v[76:77], v[100:101], 0, v[76:77]
	s_and_b64 vcc, exec, s[46:47]
	global_store_dwordx2 v[76:77], v[74:75], off
	v_mov_b32_e32 v141, 0
	v_dot2c_f32_bf16_e32 v141, v74, v74
	v_dot2c_f32_bf16_e32 v141, v75, v75
	s_nop 4
	v_add_f32_dpp v141, v141, v141 quad_perm:[1,0,3,2] row_mask:0xf bank_mask:0xf
	s_nop 1
	v_add_f32_dpp v141, v141, v141 quad_perm:[2,3,0,1] row_mask:0xf bank_mask:0xf
	s_nop 1
	v_add_f32_dpp v141, v141, v141 row_half_mirror row_mask:0xf bank_mask:0xf
	s_nop 1
	v_add_f32_dpp v141, v141, v141 row_mirror row_mask:0xf bank_mask:0xf
	v_lshl_add_u64 v[144:145], v[142:143], 0, v[146:147]
	global_store_dword v[144:145], v141, off
	s_cbranch_vccnz .LBB0_187
	s_mov_b32 s8, 0xe03f80ff
	v_mul_hi_u32 v164, v72, s8
	v_mad_u64_u32 v[74:75], s[14:15], v73, s8, v[164:165]
	v_mov_b32_e32 v164, v75
	v_mov_b32_e32 v75, v165
	s_mov_b32 s8, 0xfe03f80f
	v_mad_u64_u32 v[74:75], s[14:15], v72, s8, v[74:75]
	v_mov_b32_e32 v74, v75
	v_mov_b32_e32 v75, v165
	v_lshl_add_u64 v[74:75], v[164:165], 0, v[74:75]
	v_mad_u64_u32 v[74:75], s[14:15], v73, s8, v[74:75]
	v_alignbit_b32 v76, v75, v74, 11
	s_movk_i32 s8, 0x810
	v_mad_u64_u32 v[76:77], s[14:15], v76, s8, 0
	v_lshrrev_b32_e32 v78, 11, v75
	v_mad_u32_u24 v77, v78, s8, v77
	v_sub_co_u32_e32 v72, vcc, v72, v76
	s_nop 1
	v_subb_co_u32_e32 v73, vcc, v73, v77, vcc
	v_cmp_lt_u64_e32 vcc, 15, v[72:73]
	s_and_saveexec_b64 s[14:15], vcc
	s_cbranch_execz .LBB0_186
	v_lshrrev_b64 v[74:75], 11, v[74:75]
	v_mov_b32_e32 v76, v165
	v_mov_b32_e32 v77, v74
	v_ashrrev_i64 v[74:75], 21, v[76:77]
	v_add_u32_e32 v164, -16, v72
	v_lshl_add_u64 v[72:73], v[74:75], 0, v[164:165]
	v_lshlrev_b64 v[72:73], 12, v[72:73]
	v_lshl_add_u64 v[72:73], v[98:99], 0, v[72:73]
	global_store_dwordx4 v[72:73], v[68:71], off

; DI void epi_slab(const GemmCfg c, const f32x16 (&acc)[4], float* sW, const float* rss, const size_t row0, const int g, const int lane,
;                  float* const g_h, u16* const g_hb, float* const g_out, const int final_out) {
;     ...
;     const int c4 = l31 * 4;
;     const int col = g * 128 + c4;
;     const float sc = (K == DFF ? 0.5f : 1.f);
; #pragma unroll
;     for (int hb_ = 0; hb_ < 2; ++hb_) {
;       f32x4 hv[8];
; #pragma unroll
;       for (int i8 = 0; i8 < 8; ++i8) hv[i8] = *(const f32x4*)(g_h + (row0 + hh + 2 * (hb_ * 8 + i8)) * D + col);
; #pragma unroll
;       for (int i8 = 0; i8 < 8; ++i8) {
;         const int r = hh + 2 * (hb_ * 8 + i8);
;         const size_t row = row0 + r;
;         f32x4 v = *(const f32x4*)(sW + r * 132 + c4);
;         f32x4 o = hv[i8] + v * sc;
;         *(f32x4*)(g_h + row * D + col) = o;
;         *(u32x2*)(g_hb + row * D + col) = MK2(pack2(o[0], o[1]), pack2(o[2], o[3]));
;         if (final_out) {
;           const int b = (int)(row / T), t = (int)(row % T);
;           if (t >= 16) *(f32x4*)(g_out + ((size_t)b * 2048 + (t - 16)) * D + col) = o;
;         }
;       }
.LBB0_187:
	ds_read_b128 v[70:73], v106 offset:14784
	v_add_u32_e32 v68, 30, v128
	v_ashrrev_i32_e32 v69, 31, v68
	v_lshl_add_u64 v[68:69], s[6:7], 0, v[68:69]
	s_and_b64 vcc, exec, s[46:47]
	s_waitcnt vmcnt(21) lgkmcnt(0)
	v_pk_fma_f32 v[64:65], v[172:173], v[70:71], v[64:65]
	v_lshlrev_b64 v[70:71], 12, v[68:69]
	v_pk_fma_f32 v[66:67], v[170:171], v[72:73], v[66:67]
	v_lshl_add_u64 v[70:71], v[96:97], 0, v[70:71]
	v_lshlrev_b64 v[72:73], 11, v[68:69]
	global_store_dwordx4 v[70:71], v[64:67], off nt
	v_cvt_pk_bf16_f32 v70, v64, v65
	v_cvt_pk_bf16_f32 v71, v66, v67
	v_lshrrev_b32_e32 v142, 5, v72
	v_lshl_add_u64 v[72:73], v[100:101], 0, v[72:73]
	global_store_dwordx2 v[72:73], v[70:71], off
	v_mov_b32_e32 v141, 0
	v_dot2c_f32_bf16_e32 v141, v70, v70
	v_dot2c_f32_bf16_e32 v141, v71, v71
	s_nop 4
	v_add_f32_dpp v141, v141, v141 quad_perm:[1,0,3,2] row_mask:0xf bank_mask:0xf
	s_nop 1
	v_add_f32_dpp v141, v141, v141 quad_perm:[2,3,0,1] row_mask:0xf bank_mask:0xf
	s_nop 1
	v_add_f32_dpp v141, v141, v141 row_half_mirror row_mask:0xf bank_mask:0xf
	s_nop 1
	v_add_f32_dpp v141, v141, v141 row_mirror row_mask:0xf bank_mask:0xf
	v_lshl_add_u64 v[144:145], v[142:143], 0, v[146:147]
	global_store_dword v[144:145], v141, off
	s_cbranch_vccnz .LBB0_191
	s_mov_b32 s8, 0xe03f80ff
	v_mul_hi_u32 v164, v68, s8
	v_mad_u64_u32 v[70:71], s[14:15], v69, s8, v[164:165]
	v_mov_b32_e32 v164, v71
	v_mov_b32_e32 v71, v165
	s_mov_b32 s8, 0xfe03f80f
	v_mad_u64_u32 v[70:71], s[14:15], v68, s8, v[70:71]
	v_mov_b32_e32 v70, v71
	v_mov_b32_e32 v71, v165
	v_lshl_add_u64 v[70:71], v[164:165], 0, v[70:71]
	v_mad_u64_u32 v[70:71], s[14:15], v69, s8, v[70:71]
	v_alignbit_b32 v72, v71, v70, 11
	s_movk_i32 s8, 0x810
	v_mad_u64_u32 v[72:73], s[14:15], v72, s8, 0
	v_lshrrev_b32_e32 v74, 11, v71
	v_mad_u32_u24 v73, v74, s8, v73
	v_sub_co_u32_e32 v68, vcc, v68, v72
	s_nop 1
	v_subb_co_u32_e32 v69, vcc, v69, v73, vcc
	v_cmp_lt_u64_e32 vcc, 15, v[68:69]
	s_and_saveexec_b64 s[14:15], vcc
	s_cbranch_execz .LBB0_190
	v_lshrrev_b64 v[70:71], 11, v[70:71]
	v_mov_b32_e32 v72, v165
	v_mov_b32_e32 v73, v70
	v_ashrrev_i64 v[70:71], 21, v[72:73]
	v_add_u32_e32 v164, -16, v68
	v_lshl_add_u64 v[68:69], v[70:71], 0, v[164:165]
	v_lshlrev_b64 v[68:69], 12, v[68:69]
	v_lshl_add_u64 v[68:69], v[98:99], 0, v[68:69]
	global_store_dwordx4 v[68:69], v[64:67], off

; DI int crow(int i, int hh) { return (i & 3) + 8 * (i >> 2) + 4 * hh; }
; DI void epi_slab(const GemmCfg c, const f32x16 (&acc)[4], float* sW, const float* rss, const size_t row0, const int g, const int lane,
;                  float* const g_h, u16* const g_hb, float* const g_out, const int final_out) {
;   int ln_ = lane;
;   asm volatile("" : "+v"(ln_));
;   const int l31 = ln_ & 31, hh = ln_ >> 5;
; #pragma unroll
;   for (int nb = 0; nb < 4; ++nb)
; #pragma unroll
;     for (int i = 0; i < 16; ++i) sW[crow(i, hh) * 132 + nb * 32 + l31] = acc[nb][i];
;   asm volatile("s_waitcnt lgkmcnt(0)" ::: "memory");
;   const int K = c.K;
;   const float invK = 1.0f / (float)K;
;   if (c.epi == EPI_SWIGLU) {
.LBB0_279:
	s_andn2_b64 vcc, exec, s[44:45]
	s_cbranch_vccnz .LBB0_109
	s_waitcnt lgkmcnt(0)
	v_mov_b32_e32 v66, v185
	s_movk_i32 s8, 0x210
	v_ashrrev_i32_e32 v64, 5, v66
	v_and_b32_e32 v67, 31, v66
	v_mul_lo_u32 v68, v64, s8
	v_lshlrev_b32_e32 v65, 2, v67
	v_lshlrev_b32_e32 v69, 2, v68
	v_add3_u32 v65, s53, v65, v69
	v_lshrrev_b32_e32 v242, 4, v66
	v_mul_u32_u24_e32 v242, 0x840, v242
	v_and_b32_e32 v243, 15, v66
	v_lshl_add_u32 v242, v243, 2, v242
	v_add_u32_e32 v234, s53, v242
	v_add_u32_e32 v235, 0x210, v234
	v_add_u32_e32 v236, 0x420, v234
	v_add_u32_e32 v237, 0x630, v234
	v_add_u32_e32 v238, 0x2100, v234
	v_add_u32_e32 v239, 0x2310, v234
	v_add_u32_e32 v240, 0x2520, v234
	v_add_u32_e32 v241, 0x2730, v234
	ds_write2_b32 v234, v0, v4 offset1:16
	ds_write2_b32 v234, v8, v12 offset0:32 offset1:48
	ds_write2_b32 v234, v16, v20 offset0:64 offset1:80
	ds_write2_b32 v234, v24, v28 offset0:96 offset1:112
	ds_write2_b32 v235, v1, v5 offset1:16
	ds_write2_b32 v235, v9, v13 offset0:32 offset1:48
	ds_write2_b32 v235, v17, v21 offset0:64 offset1:80
	ds_write2_b32 v235, v25, v29 offset0:96 offset1:112
	ds_write2_b32 v236, v2, v6 offset1:16
	ds_write2_b32 v236, v10, v14 offset0:32 offset1:48
	ds_write2_b32 v236, v18, v22 offset0:64 offset1:80
	ds_write2_b32 v236, v26, v30 offset0:96 offset1:112
	ds_write2_b32 v237, v3, v7 offset1:16
	ds_write2_b32 v237, v11, v15 offset0:32 offset1:48
	ds_write2_b32 v237, v19, v23 offset0:64 offset1:80
	ds_write2_b32 v237, v27, v31 offset0:96 offset1:112
	ds_write2_b32 v238, v32, v36 offset1:16
	ds_write2_b32 v238, v40, v44 offset0:32 offset1:48
	ds_write2_b32 v238, v48, v52 offset0:64 offset1:80
	ds_write2_b32 v238, v56, v60 offset0:96 offset1:112
	ds_write2_b32 v239, v33, v37 offset1:16
	ds_write2_b32 v239, v41, v45 offset0:32 offset1:48
	ds_write2_b32 v239, v49, v53 offset0:64 offset1:80
	ds_write2_b32 v239, v57, v61 offset0:96 offset1:112
	ds_write2_b32 v240, v34, v38 offset1:16
	ds_write2_b32 v240, v42, v46 offset0:32 offset1:48
	ds_write2_b32 v240, v50, v54 offset0:64 offset1:80
	ds_write2_b32 v240, v58, v62 offset0:96 offset1:112
	ds_write2_b32 v241, v35, v39 offset1:16
	ds_write2_b32 v241, v43, v47 offset0:32 offset1:48
	ds_write2_b32 v241, v51, v55 offset0:64 offset1:80
	ds_write2_b32 v241, v59, v63 offset0:96 offset1:112
	v_add_u32_e32 v32, 0x400, v65
	v_add_u32_e32 v33, 0x1000, v65
	v_add_u32_e32 v34, 0x1400, v65
	v_add_u32_e32 v35, 0x2000, v65
	v_add_u32_e32 v36, 0x2400, v65
	v_add_u32_e32 v38, 0x3400, v65
	v_add_u32_e32 v37, 0x3000, v65
	v_add_u32_e32 v39, 0x3600, v65
	v_add_u32_e32 v0, 0x3800, v65
	s_waitcnt lgkmcnt(0)
	s_mov_b64 s[14:15], -1
	s_mov_b64 s[46:47], 0
	s_cmp_lt_i32 s52, 1
	s_mov_b64 s[8:9], 0
	s_cbranch_scc1 .LBB0_427
	s_cmp_eq_u32 s52, 1
	s_mov_b64 s[8:9], -1
	s_cbranch_scc0 .LBB0_347
; DI void epi_slab(const GemmCfg c, const f32x16 (&acc)[4], float* sW, const float* rss, const size_t row0, const int g, const int lane,
;                  float* const g_h, u16* const g_hb, float* const g_out, const int final_out) {
;     ...
;     const int c4 = l31 * 4;
;     const int col = g * 128 + c4;
;     const float sc = (K == DFF ? 0.5f : 1.f);
; #pragma unroll
;     for (int hb_ = 0; hb_ < 2; ++hb_) {
;       f32x4 hv[8];
; #pragma unroll
;       for (int i8 = 0; i8 < 8; ++i8) hv[i8] = *(const f32x4*)(g_h + (row0 + hh + 2 * (hb_ * 8 + i8)) * D + col);
; #pragma unroll
;       for (int i8 = 0; i8 < 8; ++i8) {
;         const int r = hh + 2 * (hb_ * 8 + i8);
;         const size_t row = row0 + r;
;         f32x4 v = *(const f32x4*)(sW + r * 132 + c4);
;         f32x4 o = hv[i8] + v * sc;
;         *(f32x4*)(g_h + row * D + col) = o;
;         *(u32x2*)(g_hb + row * D + col) = MK2(pack2(o[0], o[1]), pack2(o[2], o[3]));
;         if (final_out) {
;           const int b = (int)(row / T), t = (int)(row % T);
;           if (t >= 16) *(f32x4*)(g_out + ((size_t)b * 2048 + (t - 16)) * D + col) = o;
;         }
;       }
	v_lshl_or_b32 v34, v67, 2, s64
	s_or_b32 s6, s6, 32
	v_ashrrev_i32_e32 v65, 31, v64
	v_ashrrev_i32_e32 v35, 31, v34
	v_readlane_b32 s8, v254, 60
	v_lshl_add_u64 v[40:41], s[6:7], 0, v[64:65]
	v_lshlrev_b64 v[42:43], 2, v[34:35]
	v_readlane_b32 s9, v254, 61
	v_lshlrev_b64 v[0:1], 12, v[40:41]
	v_lshl_add_u32 v44, v67, 4, s53
	v_lshl_add_u64 v[32:33], s[8:9], 0, v[42:43]
	v_lshl_add_u64 v[38:39], v[32:33], 0, v[0:1]
	s_movk_i32 s8, 0x2000
	v_add_co_u32_e32 v0, vcc, s8, v38
	s_movk_i32 s8, 0x4000
	s_nop 0
	v_addc_co_u32_e32 v1, vcc, 0, v39, vcc
	global_load_dwordx4 v[28:31], v[38:39], off
	global_load_dwordx4 v[24:27], v[0:1], off
	v_add_co_u32_e32 v0, vcc, s8, v38
	s_movk_i32 s8, 0x6000
	s_nop 0
	v_addc_co_u32_e32 v1, vcc, 0, v39, vcc
	v_add_co_u32_e32 v2, vcc, s8, v38
	s_mov_b32 s8, 0x8000
	s_nop 0
	v_addc_co_u32_e32 v3, vcc, 0, v39, vcc
	global_load_dwordx4 v[20:23], v[0:1], off
	global_load_dwordx4 v[16:19], v[2:3], off
	v_add_co_u32_e32 v0, vcc, s8, v38
	s_mov_b32 s8, 0xa000
	s_nop 0
	v_addc_co_u32_e32 v1, vcc, 0, v39, vcc
	v_add_co_u32_e32 v2, vcc, s8, v38
	s_mov_b32 s8, 0xc000
	s_nop 0
	v_addc_co_u32_e32 v3, vcc, 0, v39, vcc
	global_load_dwordx4 v[12:15], v[0:1], off
	global_load_dwordx4 v[8:11], v[2:3], off
	v_add_co_u32_e32 v0, vcc, s8, v38
	s_mov_b32 s8, 0xe000
	s_nop 0
	v_addc_co_u32_e32 v1, vcc, 0, v39, vcc
	v_add_co_u32_e32 v2, vcc, s8, v38
	v_add_u32_e32 v36, v44, v68
	s_nop 0
	v_addc_co_u32_e32 v3, vcc, 0, v39, vcc
	global_load_dwordx4 v[4:7], v[0:1], off
	s_nop 0
	global_load_dwordx4 v[0:3], v[2:3], off
	v_readlane_b32 s8, v255, 3
	ds_read_b128 v[46:49], v36
	v_readlane_b32 s9, v255, 4
	v_mov_b32_e32 v171, v170
	s_waitcnt vmcnt(7) lgkmcnt(0)
	v_pk_fma_f32 v[30:31], v[170:171], v[48:49], v[30:31]
	v_lshl_add_u64 v[36:37], v[34:35], 1, s[8:9]
	v_mov_b32_e32 v148, 0x11f69000
	v_mov_b32_e32 v149, 0
	v_lshl_add_u64 v[146:147], v[148:149], 0, s[8:9]
	v_lshrrev_b32_e32 v148, 6, v34
	v_lshlrev_b32_e32 v148, 2, v148
	v_lshl_add_u64 v[146:147], v[146:147], 0, v[148:149]
	v_mov_b32_e32 v143, 0
	v_readlane_b32 s8, v252, 47
	v_readlane_b32 s9, v252, 48
	v_readlane_b32 s8, v255, 13
	v_readlane_b32 s9, v255, 14
	v_readlane_b32 s22, v252, 61
	v_readlane_b32 s23, v252, 62
	v_pk_fma_f32 v[28:29], v[172:173], v[46:47], v[28:29]
	v_lshlrev_b64 v[46:47], 11, v[40:41]
	v_cndmask_b32_e64 v45, 0, 1, s[8:9]
	v_lshl_add_u64 v[34:35], s[22:23], 0, v[42:43]
	v_cvt_pk_bf16_f32 v42, v28, v29
	v_cvt_pk_bf16_f32 v43, v30, v31
	v_lshrrev_b32_e32 v142, 5, v46
	v_lshl_add_u64 v[46:47], v[36:37], 0, v[46:47]
	v_cmp_ne_u32_e64 s[44:45], 1, v45
	s_andn2_b64 vcc, exec, s[8:9]
	v_readlane_b32 s10, v252, 49
	v_readlane_b32 s11, v252, 50
	v_readlane_b32 s12, v252, 51
	v_readlane_b32 s13, v252, 52
	v_readlane_b32 s14, v252, 53
	v_readlane_b32 s15, v252, 54
	v_readlane_b32 s16, v252, 55
	v_readlane_b32 s17, v252, 56
	v_readlane_b32 s18, v252, 57
	v_readlane_b32 s19, v252, 58
	v_readlane_b32 s20, v252, 59
	v_readlane_b32 s21, v252, 60
	global_store_dwordx4 v[38:39], v[28:31], off nt
	global_store_dwordx2 v[46:47], v[42:43], off
	v_mov_b32_e32 v141, 0
	v_dot2c_f32_bf16_e32 v141, v42, v42
	v_dot2c_f32_bf16_e32 v141, v43, v43
	s_nop 4
	v_add_f32_dpp v141, v141, v141 quad_perm:[1,0,3,2] row_mask:0xf bank_mask:0xf
	s_nop 1
	v_add_f32_dpp v141, v141, v141 quad_perm:[2,3,0,1] row_mask:0xf bank_mask:0xf
	s_nop 1
	v_add_f32_dpp v141, v141, v141 row_half_mirror row_mask:0xf bank_mask:0xf
	s_nop 1
	v_add_f32_dpp v141, v141, v141 row_mirror row_mask:0xf bank_mask:0xf
	v_lshl_add_u64 v[144:145], v[142:143], 0, v[146:147]
	global_store_dword v[144:145], v141, off
	s_cbranch_vccnz .LBB0_286
	s_mov_b32 s8, 0xe03f80ff
	v_mul_hi_u32 v164, v40, s8
	v_mad_u64_u32 v[42:43], s[8:9], v41, s8, v[164:165]
	v_mov_b32_e32 v164, v43
	v_mov_b32_e32 v43, v165
	s_mov_b32 s10, 0xfe03f80f
	v_mad_u64_u32 v[42:43], s[8:9], v40, s10, v[42:43]
	v_mov_b32_e32 v42, v43
	v_mov_b32_e32 v43, v165
	v_lshl_add_u64 v[42:43], v[164:165], 0, v[42:43]
	v_mad_u64_u32 v[42:43], s[8:9], v41, s10, v[42:43]
	v_alignbit_b32 v45, v43, v42, 11
	s_movk_i32 s10, 0x810
	v_mad_u64_u32 v[46:47], s[8:9], v45, s10, 0
	v_lshrrev_b32_e32 v45, 11, v43
	v_mad_u32_u24 v45, v45, s10, v47
	v_sub_co_u32_e32 v40, vcc, v40, v46
	s_nop 1
	v_subb_co_u32_e32 v41, vcc, v41, v45, vcc
	v_cmp_lt_u64_e32 vcc, 15, v[40:41]
	s_and_saveexec_b64 s[8:9], vcc
	s_cbranch_execz .LBB0_285
	v_lshrrev_b64 v[42:43], 11, v[42:43]
	v_mov_b32_e32 v46, v165
	v_mov_b32_e32 v47, v42
	v_ashrrev_i64 v[42:43], 21, v[46:47]
	v_add_u32_e32 v164, -16, v40
	v_lshl_add_u64 v[40:41], v[42:43], 0, v[164:165]
	v_lshlrev_b64 v[40:41], 12, v[40:41]
	v_lshl_add_u64 v[40:41], v[34:35], 0, v[40:41]
	global_store_dwordx4 v[40:41], v[28:31], off

; DI void epi_slab(const GemmCfg c, const f32x16 (&acc)[4], float* sW, const float* rss, const size_t row0, const int g, const int lane,
;                  float* const g_h, u16* const g_hb, float* const g_out, const int final_out) {
;     ...
;     const int c4 = l31 * 4;
;     const int col = g * 128 + c4;
;     const float sc = (K == DFF ? 0.5f : 1.f);
; #pragma unroll
;     for (int hb_ = 0; hb_ < 2; ++hb_) {
;       f32x4 hv[8];
; #pragma unroll
;       for (int i8 = 0; i8 < 8; ++i8) hv[i8] = *(const f32x4*)(g_h + (row0 + hh + 2 * (hb_ * 8 + i8)) * D + col);
; #pragma unroll
;       for (int i8 = 0; i8 < 8; ++i8) {
;         const int r = hh + 2 * (hb_ * 8 + i8);
;         const size_t row = row0 + r;
;         f32x4 v = *(const f32x4*)(sW + r * 132 + c4);
;         f32x4 o = hv[i8] + v * sc;
;         *(f32x4*)(g_h + row * D + col) = o;
;         *(u32x2*)(g_hb + row * D + col) = MK2(pack2(o[0], o[1]), pack2(o[2], o[3]));
;         if (final_out) {
;           const int b = (int)(row / T), t = (int)(row % T);
;           if (t >= 16) *(f32x4*)(g_out + ((size_t)b * 2048 + (t - 16)) * D + col) = o;
;         }
;       }
.LBB0_290:
	ds_read_b128 v[26:29], v42 offset:1056
	v_add_u32_e32 v24, 4, v64
	v_ashrrev_i32_e32 v25, 31, v24
	v_lshl_add_u64 v[24:25], s[6:7], 0, v[24:25]
	v_mov_b32_e32 v171, v170
	s_waitcnt vmcnt(11) lgkmcnt(0)
	v_pk_fma_f32 v[20:21], v[172:173], v[26:27], v[20:21]
	v_lshlrev_b64 v[26:27], 12, v[24:25]
	v_pk_fma_f32 v[22:23], v[170:171], v[28:29], v[22:23]
	v_lshl_add_u64 v[26:27], v[32:33], 0, v[26:27]
	v_lshlrev_b64 v[28:29], 11, v[24:25]
	global_store_dwordx4 v[26:27], v[20:23], off nt
	v_cvt_pk_bf16_f32 v26, v20, v21
	v_cvt_pk_bf16_f32 v27, v22, v23
	v_lshrrev_b32_e32 v142, 5, v28
	v_lshl_add_u64 v[28:29], v[36:37], 0, v[28:29]
	s_and_b64 vcc, exec, s[44:45]
	global_store_dwordx2 v[28:29], v[26:27], off
	v_mov_b32_e32 v141, 0
	v_dot2c_f32_bf16_e32 v141, v26, v26
	v_dot2c_f32_bf16_e32 v141, v27, v27
	s_nop 4
	v_add_f32_dpp v141, v141, v141 quad_perm:[1,0,3,2] row_mask:0xf bank_mask:0xf
	s_nop 1
	v_add_f32_dpp v141, v141, v141 quad_perm:[2,3,0,1] row_mask:0xf bank_mask:0xf
	s_nop 1
	v_add_f32_dpp v141, v141, v141 row_half_mirror row_mask:0xf bank_mask:0xf
	s_nop 1
	v_add_f32_dpp v141, v141, v141 row_mirror row_mask:0xf bank_mask:0xf
	v_lshl_add_u64 v[144:145], v[142:143], 0, v[146:147]
	global_store_dword v[144:145], v141, off
	s_cbranch_vccnz .LBB0_294
	s_mov_b32 s8, 0xe03f80ff
	v_mul_hi_u32 v164, v24, s8
	v_mad_u64_u32 v[26:27], s[8:9], v25, s8, v[164:165]
	v_mov_b32_e32 v164, v27
	v_mov_b32_e32 v27, v165
	s_mov_b32 s14, 0xfe03f80f
	v_mad_u64_u32 v[26:27], s[8:9], v24, s14, v[26:27]
	v_mov_b32_e32 v26, v27
	v_mov_b32_e32 v27, v165
	v_lshl_add_u64 v[26:27], v[164:165], 0, v[26:27]
	v_mad_u64_u32 v[26:27], s[8:9], v25, s14, v[26:27]
	v_alignbit_b32 v28, v27, v26, 11
	s_movk_i32 s14, 0x810
	v_mad_u64_u32 v[28:29], s[8:9], v28, s14, 0
	v_lshrrev_b32_e32 v30, 11, v27
	v_mad_u32_u24 v29, v30, s14, v29
	v_sub_co_u32_e32 v24, vcc, v24, v28
	s_nop 1
	v_subb_co_u32_e32 v25, vcc, v25, v29, vcc
	v_cmp_lt_u64_e32 vcc, 15, v[24:25]
	s_and_saveexec_b64 s[8:9], vcc
	s_cbranch_execz .LBB0_293
	v_lshrrev_b64 v[26:27], 11, v[26:27]
	v_mov_b32_e32 v28, v165
	v_mov_b32_e32 v29, v26
	v_ashrrev_i64 v[26:27], 21, v[28:29]
	v_add_u32_e32 v164, -16, v24
	v_lshl_add_u64 v[24:25], v[26:27], 0, v[164:165]
	v_lshlrev_b64 v[24:25], 12, v[24:25]
	v_lshl_add_u64 v[24:25], v[34:35], 0, v[24:25]
	global_store_dwordx4 v[24:25], v[20:23], off

; DI void epi_slab(const GemmCfg c, const f32x16 (&acc)[4], float* sW, const float* rss, const size_t row0, const int g, const int lane,
;                  float* const g_h, u16* const g_hb, float* const g_out, const int final_out) {
;     ...
;     const int c4 = l31 * 4;
;     const int col = g * 128 + c4;
;     const float sc = (K == DFF ? 0.5f : 1.f);
; #pragma unroll
;     for (int hb_ = 0; hb_ < 2; ++hb_) {
;       f32x4 hv[8];
; #pragma unroll
;       for (int i8 = 0; i8 < 8; ++i8) hv[i8] = *(const f32x4*)(g_h + (row0 + hh + 2 * (hb_ * 8 + i8)) * D + col);
; #pragma unroll
;       for (int i8 = 0; i8 < 8; ++i8) {
;         const int r = hh + 2 * (hb_ * 8 + i8);
;         const size_t row = row0 + r;
;         f32x4 v = *(const f32x4*)(sW + r * 132 + c4);
;         f32x4 o = hv[i8] + v * sc;
;         *(f32x4*)(g_h + row * D + col) = o;
;         *(u32x2*)(g_hb + row * D + col) = MK2(pack2(o[0], o[1]), pack2(o[2], o[3]));
;         if (final_out) {
;           const int b = (int)(row / T), t = (int)(row % T);
;           if (t >= 16) *(f32x4*)(g_out + ((size_t)b * 2048 + (t - 16)) * D + col) = o;
;         }
;       }
.LBB0_294:
	ds_read_b128 v[22:25], v42 offset:2112
	v_add_u32_e32 v20, 6, v64
	v_ashrrev_i32_e32 v21, 31, v20
	v_lshl_add_u64 v[20:21], s[6:7], 0, v[20:21]
	s_and_b64 vcc, exec, s[44:45]
	s_waitcnt vmcnt(13) lgkmcnt(0)
	v_pk_fma_f32 v[16:17], v[172:173], v[22:23], v[16:17]
	v_lshlrev_b64 v[22:23], 12, v[20:21]
	v_pk_fma_f32 v[18:19], v[170:171], v[24:25], v[18:19]
	v_lshl_add_u64 v[22:23], v[32:33], 0, v[22:23]
	v_lshlrev_b64 v[24:25], 11, v[20:21]
	global_store_dwordx4 v[22:23], v[16:19], off nt
	v_cvt_pk_bf16_f32 v22, v16, v17
	v_cvt_pk_bf16_f32 v23, v18, v19
	v_lshrrev_b32_e32 v142, 5, v24
	v_lshl_add_u64 v[24:25], v[36:37], 0, v[24:25]
	global_store_dwordx2 v[24:25], v[22:23], off
	v_mov_b32_e32 v141, 0
	v_dot2c_f32_bf16_e32 v141, v22, v22
	v_dot2c_f32_bf16_e32 v141, v23, v23
	s_nop 4
	v_add_f32_dpp v141, v141, v141 quad_perm:[1,0,3,2] row_mask:0xf bank_mask:0xf
	s_nop 1
	v_add_f32_dpp v141, v141, v141 quad_perm:[2,3,0,1] row_mask:0xf bank_mask:0xf
	s_nop 1
	v_add_f32_dpp v141, v141, v141 row_half_mirror row_mask:0xf bank_mask:0xf
	s_nop 1
	v_add_f32_dpp v141, v141, v141 row_mirror row_mask:0xf bank_mask:0xf
	v_lshl_add_u64 v[144:145], v[142:143], 0, v[146:147]
	global_store_dword v[144:145], v141, off
	s_cbranch_vccnz .LBB0_298
	s_mov_b32 s8, 0xe03f80ff
	v_mul_hi_u32 v164, v20, s8
	v_mad_u64_u32 v[22:23], s[8:9], v21, s8, v[164:165]
	v_mov_b32_e32 v164, v23
	v_mov_b32_e32 v23, v165
	s_mov_b32 s14, 0xfe03f80f
	v_mad_u64_u32 v[22:23], s[8:9], v20, s14, v[22:23]
	v_mov_b32_e32 v22, v23
	v_mov_b32_e32 v23, v165
	v_lshl_add_u64 v[22:23], v[164:165], 0, v[22:23]
	v_mad_u64_u32 v[22:23], s[8:9], v21, s14, v[22:23]
	v_alignbit_b32 v24, v23, v22, 11
	s_movk_i32 s14, 0x810
	v_mad_u64_u32 v[24:25], s[8:9], v24, s14, 0
	v_lshrrev_b32_e32 v26, 11, v23
	v_mad_u32_u24 v25, v26, s14, v25
	v_sub_co_u32_e32 v20, vcc, v20, v24
	s_nop 1
	v_subb_co_u32_e32 v21, vcc, v21, v25, vcc
	v_cmp_lt_u64_e32 vcc, 15, v[20:21]
	s_and_saveexec_b64 s[8:9], vcc
	s_cbranch_execz .LBB0_297
	v_lshrrev_b64 v[22:23], 11, v[22:23]
	v_mov_b32_e32 v24, v165
	v_mov_b32_e32 v25, v22
	v_ashrrev_i64 v[22:23], 21, v[24:25]
	v_add_u32_e32 v164, -16, v20
	v_lshl_add_u64 v[20:21], v[22:23], 0, v[164:165]
	v_lshlrev_b64 v[20:21], 12, v[20:21]
	v_lshl_add_u64 v[20:21], v[34:35], 0, v[20:21]
	global_store_dwordx4 v[20:21], v[16:19], off

; DI void epi_slab(const GemmCfg c, const f32x16 (&acc)[4], float* sW, const float* rss, const size_t row0, const int g, const int lane,
;                  float* const g_h, u16* const g_hb, float* const g_out, const int final_out) {
;     ...
;     const int c4 = l31 * 4;
;     const int col = g * 128 + c4;
;     const float sc = (K == DFF ? 0.5f : 1.f);
; #pragma unroll
;     for (int hb_ = 0; hb_ < 2; ++hb_) {
;       f32x4 hv[8];
; #pragma unroll
;       for (int i8 = 0; i8 < 8; ++i8) hv[i8] = *(const f32x4*)(g_h + (row0 + hh + 2 * (hb_ * 8 + i8)) * D + col);
; #pragma unroll
;       for (int i8 = 0; i8 < 8; ++i8) {
;         const int r = hh + 2 * (hb_ * 8 + i8);
;         const size_t row = row0 + r;
;         f32x4 v = *(const f32x4*)(sW + r * 132 + c4);
;         f32x4 o = hv[i8] + v * sc;
;         *(f32x4*)(g_h + row * D + col) = o;
;         *(u32x2*)(g_hb + row * D + col) = MK2(pack2(o[0], o[1]), pack2(o[2], o[3]));
;         if (final_out) {
;           const int b = (int)(row / T), t = (int)(row % T);
;           if (t >= 16) *(f32x4*)(g_out + ((size_t)b * 2048 + (t - 16)) * D + col) = o;
;         }
;       }
.LBB0_298:
	ds_read_b128 v[18:21], v42 offset:3168
	v_add_u32_e32 v16, 8, v64
	v_ashrrev_i32_e32 v17, 31, v16
	v_lshl_add_u64 v[16:17], s[6:7], 0, v[16:17]
	v_mov_b32_e32 v171, v170
	s_waitcnt vmcnt(15) lgkmcnt(0)
	v_pk_fma_f32 v[12:13], v[172:173], v[18:19], v[12:13]
	v_lshlrev_b64 v[18:19], 12, v[16:17]
	v_pk_fma_f32 v[14:15], v[170:171], v[20:21], v[14:15]
	v_lshl_add_u64 v[18:19], v[32:33], 0, v[18:19]
	v_lshlrev_b64 v[20:21], 11, v[16:17]
	global_store_dwordx4 v[18:19], v[12:15], off nt
	v_cvt_pk_bf16_f32 v18, v12, v13
	v_cvt_pk_bf16_f32 v19, v14, v15
	v_lshrrev_b32_e32 v142, 5, v20
	v_lshl_add_u64 v[20:21], v[36:37], 0, v[20:21]
	s_and_b64 vcc, exec, s[44:45]
	global_store_dwordx2 v[20:21], v[18:19], off
	v_mov_b32_e32 v141, 0
	v_dot2c_f32_bf16_e32 v141, v18, v18
	v_dot2c_f32_bf16_e32 v141, v19, v19
	s_nop 4
	v_add_f32_dpp v141, v141, v141 quad_perm:[1,0,3,2] row_mask:0xf bank_mask:0xf
	s_nop 1
	v_add_f32_dpp v141, v141, v141 quad_perm:[2,3,0,1] row_mask:0xf bank_mask:0xf
	s_nop 1
	v_add_f32_dpp v141, v141, v141 row_half_mirror row_mask:0xf bank_mask:0xf
	s_nop 1
	v_add_f32_dpp v141, v141, v141 row_mirror row_mask:0xf bank_mask:0xf
	v_lshl_add_u64 v[144:145], v[142:143], 0, v[146:147]
	global_store_dword v[144:145], v141, off
	s_cbranch_vccnz .LBB0_302
	s_mov_b32 s8, 0xe03f80ff
	v_mul_hi_u32 v164, v16, s8
	v_mad_u64_u32 v[18:19], s[8:9], v17, s8, v[164:165]
	v_mov_b32_e32 v164, v19
	v_mov_b32_e32 v19, v165
	s_mov_b32 s14, 0xfe03f80f
	v_mad_u64_u32 v[18:19], s[8:9], v16, s14, v[18:19]
	v_mov_b32_e32 v18, v19
	v_mov_b32_e32 v19, v165
	v_lshl_add_u64 v[18:19], v[164:165], 0, v[18:19]
	v_mad_u64_u32 v[18:19], s[8:9], v17, s14, v[18:19]
	v_alignbit_b32 v20, v19, v18, 11
	s_movk_i32 s14, 0x810
	v_mad_u64_u32 v[20:21], s[8:9], v20, s14, 0
	v_lshrrev_b32_e32 v22, 11, v19
	v_mad_u32_u24 v21, v22, s14, v21
	v_sub_co_u32_e32 v16, vcc, v16, v20
	s_nop 1
	v_subb_co_u32_e32 v17, vcc, v17, v21, vcc
	v_cmp_lt_u64_e32 vcc, 15, v[16:17]
	s_and_saveexec_b64 s[8:9], vcc
	s_cbranch_execz .LBB0_301
	v_lshrrev_b64 v[18:19], 11, v[18:19]
	v_mov_b32_e32 v20, v165
	v_mov_b32_e32 v21, v18
	v_ashrrev_i64 v[18:19], 21, v[20:21]
	v_add_u32_e32 v164, -16, v16
	v_lshl_add_u64 v[16:17], v[18:19], 0, v[164:165]
	v_lshlrev_b64 v[16:17], 12, v[16:17]
	v_lshl_add_u64 v[16:17], v[34:35], 0, v[16:17]
	global_store_dwordx4 v[16:17], v[12:15], off

; DI void epi_slab(const GemmCfg c, const f32x16 (&acc)[4], float* sW, const float* rss, const size_t row0, const int g, const int lane,
;                  float* const g_h, u16* const g_hb, float* const g_out, const int final_out) {
;     ...
;     const int c4 = l31 * 4;
;     const int col = g * 128 + c4;
;     const float sc = (K == DFF ? 0.5f : 1.f);
; #pragma unroll
;     for (int hb_ = 0; hb_ < 2; ++hb_) {
;       f32x4 hv[8];
; #pragma unroll
;       for (int i8 = 0; i8 < 8; ++i8) hv[i8] = *(const f32x4*)(g_h + (row0 + hh + 2 * (hb_ * 8 + i8)) * D + col);
; #pragma unroll
;       for (int i8 = 0; i8 < 8; ++i8) {
;         const int r = hh + 2 * (hb_ * 8 + i8);
;         const size_t row = row0 + r;
;         f32x4 v = *(const f32x4*)(sW + r * 132 + c4);
;         f32x4 o = hv[i8] + v * sc;
;         *(f32x4*)(g_h + row * D + col) = o;
;         *(u32x2*)(g_hb + row * D + col) = MK2(pack2(o[0], o[1]), pack2(o[2], o[3]));
;         if (final_out) {
;           const int b = (int)(row / T), t = (int)(row % T);
;           if (t >= 16) *(f32x4*)(g_out + ((size_t)b * 2048 + (t - 16)) * D + col) = o;
;         }
;       }
.LBB0_302:
	ds_read_b128 v[14:17], v42 offset:4224
	v_add_u32_e32 v12, 10, v64
	v_ashrrev_i32_e32 v13, 31, v12
	v_lshl_add_u64 v[12:13], s[6:7], 0, v[12:13]
	s_and_b64 vcc, exec, s[44:45]
	s_waitcnt vmcnt(17) lgkmcnt(0)
	v_pk_fma_f32 v[8:9], v[172:173], v[14:15], v[8:9]
	v_lshlrev_b64 v[14:15], 12, v[12:13]
	v_pk_fma_f32 v[10:11], v[170:171], v[16:17], v[10:11]
	v_lshl_add_u64 v[14:15], v[32:33], 0, v[14:15]
	v_lshlrev_b64 v[16:17], 11, v[12:13]
	global_store_dwordx4 v[14:15], v[8:11], off nt
	v_cvt_pk_bf16_f32 v14, v8, v9
	v_cvt_pk_bf16_f32 v15, v10, v11
	v_lshrrev_b32_e32 v142, 5, v16
	v_lshl_add_u64 v[16:17], v[36:37], 0, v[16:17]
	global_store_dwordx2 v[16:17], v[14:15], off
	v_mov_b32_e32 v141, 0
	v_dot2c_f32_bf16_e32 v141, v14, v14
	v_dot2c_f32_bf16_e32 v141, v15, v15
	s_nop 4
	v_add_f32_dpp v141, v141, v141 quad_perm:[1,0,3,2] row_mask:0xf bank_mask:0xf
	s_nop 1
	v_add_f32_dpp v141, v141, v141 quad_perm:[2,3,0,1] row_mask:0xf bank_mask:0xf
	s_nop 1
	v_add_f32_dpp v141, v141, v141 row_half_mirror row_mask:0xf bank_mask:0xf
	s_nop 1
	v_add_f32_dpp v141, v141, v141 row_mirror row_mask:0xf bank_mask:0xf
	v_lshl_add_u64 v[144:145], v[142:143], 0, v[146:147]
	global_store_dword v[144:145], v141, off
	s_cbranch_vccnz .LBB0_306
	s_mov_b32 s8, 0xe03f80ff
	v_mul_hi_u32 v164, v12, s8
	v_mad_u64_u32 v[14:15], s[8:9], v13, s8, v[164:165]
	v_mov_b32_e32 v164, v15
	v_mov_b32_e32 v15, v165
	s_mov_b32 s14, 0xfe03f80f
	v_mad_u64_u32 v[14:15], s[8:9], v12, s14, v[14:15]
	v_mov_b32_e32 v14, v15
	v_mov_b32_e32 v15, v165
	v_lshl_add_u64 v[14:15], v[164:165], 0, v[14:15]
	v_mad_u64_u32 v[14:15], s[8:9], v13, s14, v[14:15]
	v_alignbit_b32 v16, v15, v14, 11
	s_movk_i32 s14, 0x810
	v_mad_u64_u32 v[16:17], s[8:9], v16, s14, 0
	v_lshrrev_b32_e32 v18, 11, v15
	v_mad_u32_u24 v17, v18, s14, v17
	v_sub_co_u32_e32 v12, vcc, v12, v16
	s_nop 1
	v_subb_co_u32_e32 v13, vcc, v13, v17, vcc
	v_cmp_lt_u64_e32 vcc, 15, v[12:13]
	s_and_saveexec_b64 s[8:9], vcc
	s_cbranch_execz .LBB0_305
	v_lshrrev_b64 v[14:15], 11, v[14:15]
	v_mov_b32_e32 v16, v165
	v_mov_b32_e32 v17, v14
	v_ashrrev_i64 v[14:15], 21, v[16:17]
	v_add_u32_e32 v164, -16, v12
	v_lshl_add_u64 v[12:13], v[14:15], 0, v[164:165]
	v_lshlrev_b64 v[12:13], 12, v[12:13]
	v_lshl_add_u64 v[12:13], v[34:35], 0, v[12:13]
	global_store_dwordx4 v[12:13], v[8:11], off

; DI void epi_slab(const GemmCfg c, const f32x16 (&acc)[4], float* sW, const float* rss, const size_t row0, const int g, const int lane,
;                  float* const g_h, u16* const g_hb, float* const g_out, const int final_out) {
;     ...
;     const int c4 = l31 * 4;
;     const int col = g * 128 + c4;
;     const float sc = (K == DFF ? 0.5f : 1.f);
; #pragma unroll
;     for (int hb_ = 0; hb_ < 2; ++hb_) {
;       f32x4 hv[8];
; #pragma unroll
;       for (int i8 = 0; i8 < 8; ++i8) hv[i8] = *(const f32x4*)(g_h + (row0 + hh + 2 * (hb_ * 8 + i8)) * D + col);
; #pragma unroll
;       for (int i8 = 0; i8 < 8; ++i8) {
;         const int r = hh + 2 * (hb_ * 8 + i8);
;         const size_t row = row0 + r;
;         f32x4 v = *(const f32x4*)(sW + r * 132 + c4);
;         f32x4 o = hv[i8] + v * sc;
;         *(f32x4*)(g_h + row * D + col) = o;
;         *(u32x2*)(g_hb + row * D + col) = MK2(pack2(o[0], o[1]), pack2(o[2], o[3]));
;         if (final_out) {
;           const int b = (int)(row / T), t = (int)(row % T);
;           if (t >= 16) *(f32x4*)(g_out + ((size_t)b * 2048 + (t - 16)) * D + col) = o;
;         }
;       }
.LBB0_306:
	ds_read_b128 v[10:13], v42 offset:5280
	v_add_u32_e32 v8, 12, v64
	v_ashrrev_i32_e32 v9, 31, v8
	v_lshl_add_u64 v[8:9], s[6:7], 0, v[8:9]
	v_mov_b32_e32 v171, v170
	s_waitcnt vmcnt(19) lgkmcnt(0)
	v_pk_fma_f32 v[4:5], v[172:173], v[10:11], v[4:5]
	v_lshlrev_b64 v[10:11], 12, v[8:9]
	v_pk_fma_f32 v[6:7], v[170:171], v[12:13], v[6:7]
	v_lshl_add_u64 v[10:11], v[32:33], 0, v[10:11]
	v_lshlrev_b64 v[12:13], 11, v[8:9]
	global_store_dwordx4 v[10:11], v[4:7], off nt
	v_cvt_pk_bf16_f32 v10, v4, v5
	v_cvt_pk_bf16_f32 v11, v6, v7
	v_lshrrev_b32_e32 v142, 5, v12
	v_lshl_add_u64 v[12:13], v[36:37], 0, v[12:13]
	s_and_b64 vcc, exec, s[44:45]
	global_store_dwordx2 v[12:13], v[10:11], off
	v_mov_b32_e32 v141, 0
	v_dot2c_f32_bf16_e32 v141, v10, v10
	v_dot2c_f32_bf16_e32 v141, v11, v11
	s_nop 4
	v_add_f32_dpp v141, v141, v141 quad_perm:[1,0,3,2] row_mask:0xf bank_mask:0xf
	s_nop 1
	v_add_f32_dpp v141, v141, v141 quad_perm:[2,3,0,1] row_mask:0xf bank_mask:0xf
	s_nop 1
	v_add_f32_dpp v141, v141, v141 row_half_mirror row_mask:0xf bank_mask:0xf
	s_nop 1
	v_add_f32_dpp v141, v141, v141 row_mirror row_mask:0xf bank_mask:0xf
	v_lshl_add_u64 v[144:145], v[142:143], 0, v[146:147]
	global_store_dword v[144:145], v141, off
	s_cbranch_vccnz .LBB0_310
	s_mov_b32 s8, 0xe03f80ff
	v_mul_hi_u32 v164, v8, s8
	v_mad_u64_u32 v[10:11], s[8:9], v9, s8, v[164:165]
	v_mov_b32_e32 v164, v11
	v_mov_b32_e32 v11, v165
	s_mov_b32 s14, 0xfe03f80f
	v_mad_u64_u32 v[10:11], s[8:9], v8, s14, v[10:11]
	v_mov_b32_e32 v10, v11
	v_mov_b32_e32 v11, v165
	v_lshl_add_u64 v[10:11], v[164:165], 0, v[10:11]
	v_mad_u64_u32 v[10:11], s[8:9], v9, s14, v[10:11]
	v_alignbit_b32 v12, v11, v10, 11
	s_movk_i32 s14, 0x810
	v_mad_u64_u32 v[12:13], s[8:9], v12, s14, 0
	v_lshrrev_b32_e32 v14, 11, v11
	v_mad_u32_u24 v13, v14, s14, v13
	v_sub_co_u32_e32 v8, vcc, v8, v12
	s_nop 1
	v_subb_co_u32_e32 v9, vcc, v9, v13, vcc
	v_cmp_lt_u64_e32 vcc, 15, v[8:9]
	s_and_saveexec_b64 s[8:9], vcc
	s_cbranch_execz .LBB0_309
	v_lshrrev_b64 v[10:11], 11, v[10:11]
	v_mov_b32_e32 v12, v165
	v_mov_b32_e32 v13, v10
	v_ashrrev_i64 v[10:11], 21, v[12:13]
	v_add_u32_e32 v164, -16, v8
	v_lshl_add_u64 v[8:9], v[10:11], 0, v[164:165]
	v_lshlrev_b64 v[8:9], 12, v[8:9]
	v_lshl_add_u64 v[8:9], v[34:35], 0, v[8:9]
	global_store_dwordx4 v[8:9], v[4:7], off

; DI void epi_slab(const GemmCfg c, const f32x16 (&acc)[4], float* sW, const float* rss, const size_t row0, const int g, const int lane,
;                  float* const g_h, u16* const g_hb, float* const g_out, const int final_out) {
;     ...
;     const int c4 = l31 * 4;
;     const int col = g * 128 + c4;
;     const float sc = (K == DFF ? 0.5f : 1.f);
; #pragma unroll
;     for (int hb_ = 0; hb_ < 2; ++hb_) {
;       f32x4 hv[8];
; #pragma unroll
;       for (int i8 = 0; i8 < 8; ++i8) hv[i8] = *(const f32x4*)(g_h + (row0 + hh + 2 * (hb_ * 8 + i8)) * D + col);
; #pragma unroll
;       for (int i8 = 0; i8 < 8; ++i8) {
;         const int r = hh + 2 * (hb_ * 8 + i8);
;         const size_t row = row0 + r;
;         f32x4 v = *(const f32x4*)(sW + r * 132 + c4);
;         f32x4 o = hv[i8] + v * sc;
;         *(f32x4*)(g_h + row * D + col) = o;
;         *(u32x2*)(g_hb + row * D + col) = MK2(pack2(o[0], o[1]), pack2(o[2], o[3]));
;         if (final_out) {
;           const int b = (int)(row / T), t = (int)(row % T);
;           if (t >= 16) *(f32x4*)(g_out + ((size_t)b * 2048 + (t - 16)) * D + col) = o;
;         }
;       }
.LBB0_310:
	ds_read_b128 v[6:9], v42 offset:6336
	v_add_u32_e32 v4, 14, v64
	v_ashrrev_i32_e32 v5, 31, v4
	v_lshl_add_u64 v[4:5], s[6:7], 0, v[4:5]
	s_and_b64 vcc, exec, s[44:45]
	s_waitcnt vmcnt(21) lgkmcnt(0)
	v_pk_fma_f32 v[0:1], v[172:173], v[6:7], v[0:1]
	v_lshlrev_b64 v[6:7], 12, v[4:5]
	v_pk_fma_f32 v[2:3], v[170:171], v[8:9], v[2:3]
	v_lshl_add_u64 v[6:7], v[32:33], 0, v[6:7]
	v_lshlrev_b64 v[8:9], 11, v[4:5]
	global_store_dwordx4 v[6:7], v[0:3], off nt
	v_cvt_pk_bf16_f32 v6, v0, v1
	v_cvt_pk_bf16_f32 v7, v2, v3
	v_lshrrev_b32_e32 v142, 5, v8
	v_lshl_add_u64 v[8:9], v[36:37], 0, v[8:9]
	global_store_dwordx2 v[8:9], v[6:7], off
	v_mov_b32_e32 v141, 0
	v_dot2c_f32_bf16_e32 v141, v6, v6
	v_dot2c_f32_bf16_e32 v141, v7, v7
	s_nop 4
	v_add_f32_dpp v141, v141, v141 quad_perm:[1,0,3,2] row_mask:0xf bank_mask:0xf
	s_nop 1
	v_add_f32_dpp v141, v141, v141 quad_perm:[2,3,0,1] row_mask:0xf bank_mask:0xf
	s_nop 1
	v_add_f32_dpp v141, v141, v141 row_half_mirror row_mask:0xf bank_mask:0xf
	s_nop 1
	v_add_f32_dpp v141, v141, v141 row_mirror row_mask:0xf bank_mask:0xf
	v_lshl_add_u64 v[144:145], v[142:143], 0, v[146:147]
	global_store_dword v[144:145], v141, off
	s_cbranch_vccnz .LBB0_314
	s_mov_b32 s8, 0xe03f80ff
	v_mul_hi_u32 v164, v4, s8
	v_mad_u64_u32 v[6:7], s[8:9], v5, s8, v[164:165]
	v_mov_b32_e32 v164, v7
	v_mov_b32_e32 v7, v165
	s_mov_b32 s14, 0xfe03f80f
	v_mad_u64_u32 v[6:7], s[8:9], v4, s14, v[6:7]
	v_mov_b32_e32 v6, v7
	v_mov_b32_e32 v7, v165
	v_lshl_add_u64 v[6:7], v[164:165], 0, v[6:7]
	v_mad_u64_u32 v[6:7], s[8:9], v5, s14, v[6:7]
	v_alignbit_b32 v8, v7, v6, 11
	s_movk_i32 s14, 0x810
	v_mad_u64_u32 v[8:9], s[8:9], v8, s14, 0
	v_lshrrev_b32_e32 v10, 11, v7
	v_mad_u32_u24 v9, v10, s14, v9
	v_sub_co_u32_e32 v4, vcc, v4, v8
	s_nop 1
	v_subb_co_u32_e32 v5, vcc, v5, v9, vcc
	v_cmp_lt_u64_e32 vcc, 15, v[4:5]
	s_and_saveexec_b64 s[8:9], vcc
	s_cbranch_execz .LBB0_313
	v_lshrrev_b64 v[6:7], 11, v[6:7]
	v_mov_b32_e32 v8, v165
	v_mov_b32_e32 v9, v6
	v_ashrrev_i64 v[6:7], 21, v[8:9]
	v_add_u32_e32 v164, -16, v4
	v_lshl_add_u64 v[4:5], v[6:7], 0, v[164:165]
	v_lshlrev_b64 v[4:5], 12, v[4:5]
	v_lshl_add_u64 v[4:5], v[34:35], 0, v[4:5]
	global_store_dwordx4 v[4:5], v[0:3], off

; DI void epi_slab(const GemmCfg c, const f32x16 (&acc)[4], float* sW, const float* rss, const size_t row0, const int g, const int lane,
;                  float* const g_h, u16* const g_hb, float* const g_out, const int final_out) {
;     ...
;     const int c4 = l31 * 4;
;     const int col = g * 128 + c4;
;     const float sc = (K == DFF ? 0.5f : 1.f);
; #pragma unroll
;     for (int hb_ = 0; hb_ < 2; ++hb_) {
;       f32x4 hv[8];
; #pragma unroll
;       for (int i8 = 0; i8 < 8; ++i8) hv[i8] = *(const f32x4*)(g_h + (row0 + hh + 2 * (hb_ * 8 + i8)) * D + col);
; #pragma unroll
;       for (int i8 = 0; i8 < 8; ++i8) {
;         const int r = hh + 2 * (hb_ * 8 + i8);
;         const size_t row = row0 + r;
;         f32x4 v = *(const f32x4*)(sW + r * 132 + c4);
;         f32x4 o = hv[i8] + v * sc;
;         *(f32x4*)(g_h + row * D + col) = o;
;         *(u32x2*)(g_hb + row * D + col) = MK2(pack2(o[0], o[1]), pack2(o[2], o[3]));
;         if (final_out) {
;           const int b = (int)(row / T), t = (int)(row % T);
;           if (t >= 16) *(f32x4*)(g_out + ((size_t)b * 2048 + (t - 16)) * D + col) = o;
;         }
;       }
.LBB0_314:
	s_nop 0
	v_add_co_u32_e32 v0, vcc, 0x10000, v38
	ds_read_b128 v[44:47], v42 offset:7392
	s_nop 0
	v_addc_co_u32_e32 v1, vcc, 0, v39, vcc
	global_load_dwordx4 v[28:31], v[0:1], off
	v_add_co_u32_e32 v0, vcc, 0x12000, v38
	v_mov_b32_e32 v171, v170
	s_nop 0
	v_addc_co_u32_e32 v1, vcc, 0, v39, vcc
	global_load_dwordx4 v[24:27], v[0:1], off
	v_add_co_u32_e32 v0, vcc, 0x14000, v38
	s_waitcnt vmcnt(1) lgkmcnt(0)
	v_pk_fma_f32 v[30:31], v[170:171], v[46:47], v[30:31]
	v_addc_co_u32_e32 v1, vcc, 0, v39, vcc
	global_load_dwordx4 v[20:23], v[0:1], off
	v_add_co_u32_e32 v0, vcc, 0x16000, v38
	v_pk_fma_f32 v[28:29], v[172:173], v[44:45], v[28:29]
	s_nop 0
	v_addc_co_u32_e32 v1, vcc, 0, v39, vcc
	global_load_dwordx4 v[16:19], v[0:1], off
	v_add_co_u32_e32 v0, vcc, 0x18000, v38
	s_nop 1
	v_addc_co_u32_e32 v1, vcc, 0, v39, vcc
	global_load_dwordx4 v[12:15], v[0:1], off
	v_add_co_u32_e32 v0, vcc, 0x1a000, v38
	s_nop 1
	v_addc_co_u32_e32 v1, vcc, 0, v39, vcc
	global_load_dwordx4 v[8:11], v[0:1], off
	v_add_co_u32_e32 v0, vcc, 0x1c000, v38
	s_nop 1
	v_addc_co_u32_e32 v1, vcc, 0, v39, vcc
	global_load_dwordx4 v[4:7], v[0:1], off
	v_add_co_u32_e32 v0, vcc, 0x1e000, v38
	v_add_u32_e32 v38, 16, v64
	s_nop 0
	v_addc_co_u32_e32 v1, vcc, 0, v39, vcc
	global_load_dwordx4 v[0:3], v[0:1], off
	v_ashrrev_i32_e32 v39, 31, v38
	v_lshl_add_u64 v[38:39], s[6:7], 0, v[38:39]
	v_lshlrev_b64 v[40:41], 12, v[38:39]
	v_lshl_add_u64 v[40:41], v[32:33], 0, v[40:41]
	v_lshlrev_b64 v[44:45], 11, v[38:39]
	global_store_dwordx4 v[40:41], v[28:31], off nt
	v_cvt_pk_bf16_f32 v40, v28, v29
	v_cvt_pk_bf16_f32 v41, v30, v31
	v_lshrrev_b32_e32 v142, 5, v44
	v_lshl_add_u64 v[44:45], v[36:37], 0, v[44:45]
	s_and_b64 vcc, exec, s[44:45]
	global_store_dwordx2 v[44:45], v[40:41], off
	v_mov_b32_e32 v141, 0
	v_dot2c_f32_bf16_e32 v141, v40, v40
	v_dot2c_f32_bf16_e32 v141, v41, v41
	s_nop 4
	v_add_f32_dpp v141, v141, v141 quad_perm:[1,0,3,2] row_mask:0xf bank_mask:0xf
	s_nop 1
	v_add_f32_dpp v141, v141, v141 quad_perm:[2,3,0,1] row_mask:0xf bank_mask:0xf
	s_nop 1
	v_add_f32_dpp v141, v141, v141 row_half_mirror row_mask:0xf bank_mask:0xf
	s_nop 1
	v_add_f32_dpp v141, v141, v141 row_mirror row_mask:0xf bank_mask:0xf
	v_lshl_add_u64 v[144:145], v[142:143], 0, v[146:147]
	global_store_dword v[144:145], v141, off
	s_cbranch_vccnz .LBB0_318
	s_mov_b32 s8, 0xe03f80ff
	v_mul_hi_u32 v164, v38, s8
	v_mad_u64_u32 v[40:41], s[8:9], v39, s8, v[164:165]
	v_mov_b32_e32 v164, v41
	v_mov_b32_e32 v41, v165
	s_mov_b32 s14, 0xfe03f80f
	v_mad_u64_u32 v[40:41], s[8:9], v38, s14, v[40:41]
	v_mov_b32_e32 v40, v41
	v_mov_b32_e32 v41, v165
	v_lshl_add_u64 v[40:41], v[164:165], 0, v[40:41]
	v_mad_u64_u32 v[40:41], s[8:9], v39, s14, v[40:41]
	v_alignbit_b32 v43, v41, v40, 11
	s_movk_i32 s14, 0x810
	v_mad_u64_u32 v[44:45], s[8:9], v43, s14, 0
	v_lshrrev_b32_e32 v43, 11, v41
	v_mad_u32_u24 v43, v43, s14, v45
	v_sub_co_u32_e32 v38, vcc, v38, v44
	s_nop 1
	v_subb_co_u32_e32 v39, vcc, v39, v43, vcc
	v_cmp_lt_u64_e32 vcc, 15, v[38:39]
	s_and_saveexec_b64 s[8:9], vcc
	s_cbranch_execz .LBB0_317
	v_lshrrev_b64 v[40:41], 11, v[40:41]
	v_mov_b32_e32 v44, v165
	v_mov_b32_e32 v45, v40
	v_ashrrev_i64 v[40:41], 21, v[44:45]
	v_add_u32_e32 v164, -16, v38
	v_lshl_add_u64 v[38:39], v[40:41], 0, v[164:165]
	v_lshlrev_b64 v[38:39], 12, v[38:39]
	v_lshl_add_u64 v[38:39], v[34:35], 0, v[38:39]
	global_store_dwordx4 v[38:39], v[28:31], off

; DI void epi_slab(const GemmCfg c, const f32x16 (&acc)[4], float* sW, const float* rss, const size_t row0, const int g, const int lane,
;                  float* const g_h, u16* const g_hb, float* const g_out, const int final_out) {
;     ...
;     const int c4 = l31 * 4;
;     const int col = g * 128 + c4;
;     const float sc = (K == DFF ? 0.5f : 1.f);
; #pragma unroll
;     for (int hb_ = 0; hb_ < 2; ++hb_) {
;       f32x4 hv[8];
; #pragma unroll
;       for (int i8 = 0; i8 < 8; ++i8) hv[i8] = *(const f32x4*)(g_h + (row0 + hh + 2 * (hb_ * 8 + i8)) * D + col);
; #pragma unroll
;       for (int i8 = 0; i8 < 8; ++i8) {
;         const int r = hh + 2 * (hb_ * 8 + i8);
;         const size_t row = row0 + r;
;         f32x4 v = *(const f32x4*)(sW + r * 132 + c4);
;         f32x4 o = hv[i8] + v * sc;
;         *(f32x4*)(g_h + row * D + col) = o;
;         *(u32x2*)(g_hb + row * D + col) = MK2(pack2(o[0], o[1]), pack2(o[2], o[3]));
;         if (final_out) {
;           const int b = (int)(row / T), t = (int)(row % T);
;           if (t >= 16) *(f32x4*)(g_out + ((size_t)b * 2048 + (t - 16)) * D + col) = o;
;         }
;       }
.LBB0_318:
	ds_read_b128 v[38:41], v42 offset:8448
	v_add_u32_e32 v28, 18, v64
	v_ashrrev_i32_e32 v29, 31, v28
	v_lshl_add_u64 v[28:29], s[6:7], 0, v[28:29]
	v_lshlrev_b64 v[30:31], 12, v[28:29]
	s_waitcnt vmcnt(9) lgkmcnt(0)
	v_pk_fma_f32 v[26:27], v[170:171], v[40:41], v[26:27]
	v_pk_fma_f32 v[24:25], v[172:173], v[38:39], v[24:25]
	v_lshl_add_u64 v[30:31], v[32:33], 0, v[30:31]
	v_lshlrev_b64 v[38:39], 11, v[28:29]
	global_store_dwordx4 v[30:31], v[24:27], off nt
	v_cvt_pk_bf16_f32 v30, v24, v25
	v_cvt_pk_bf16_f32 v31, v26, v27
	v_lshrrev_b32_e32 v142, 5, v38
	v_lshl_add_u64 v[38:39], v[36:37], 0, v[38:39]
	s_and_b64 vcc, exec, s[44:45]
	global_store_dwordx2 v[38:39], v[30:31], off
	v_mov_b32_e32 v141, 0
	v_dot2c_f32_bf16_e32 v141, v30, v30
	v_dot2c_f32_bf16_e32 v141, v31, v31
	s_nop 4
	v_add_f32_dpp v141, v141, v141 quad_perm:[1,0,3,2] row_mask:0xf bank_mask:0xf
	s_nop 1
	v_add_f32_dpp v141, v141, v141 quad_perm:[2,3,0,1] row_mask:0xf bank_mask:0xf
	s_nop 1
	v_add_f32_dpp v141, v141, v141 row_half_mirror row_mask:0xf bank_mask:0xf
	s_nop 1
	v_add_f32_dpp v141, v141, v141 row_mirror row_mask:0xf bank_mask:0xf
	v_lshl_add_u64 v[144:145], v[142:143], 0, v[146:147]
	global_store_dword v[144:145], v141, off
	s_cbranch_vccnz .LBB0_322
	s_mov_b32 s8, 0xe03f80ff
	v_mul_hi_u32 v164, v28, s8
	v_mad_u64_u32 v[30:31], s[8:9], v29, s8, v[164:165]
	v_mov_b32_e32 v164, v31
	v_mov_b32_e32 v31, v165
	s_mov_b32 s14, 0xfe03f80f
	v_mad_u64_u32 v[30:31], s[8:9], v28, s14, v[30:31]
	v_mov_b32_e32 v30, v31
	v_mov_b32_e32 v31, v165
	v_lshl_add_u64 v[30:31], v[164:165], 0, v[30:31]
	v_mad_u64_u32 v[30:31], s[8:9], v29, s14, v[30:31]
	v_alignbit_b32 v38, v31, v30, 11
	s_movk_i32 s14, 0x810
	v_mad_u64_u32 v[38:39], s[8:9], v38, s14, 0
	v_lshrrev_b32_e32 v40, 11, v31
	v_mad_u32_u24 v39, v40, s14, v39
	v_sub_co_u32_e32 v28, vcc, v28, v38
	s_nop 1
	v_subb_co_u32_e32 v29, vcc, v29, v39, vcc
	v_cmp_lt_u64_e32 vcc, 15, v[28:29]
	s_and_saveexec_b64 s[8:9], vcc
	s_cbranch_execz .LBB0_321
	v_lshrrev_b64 v[30:31], 11, v[30:31]
	v_mov_b32_e32 v38, v165
	v_mov_b32_e32 v39, v30
	v_ashrrev_i64 v[30:31], 21, v[38:39]
	v_add_u32_e32 v164, -16, v28
	v_lshl_add_u64 v[28:29], v[30:31], 0, v[164:165]
	v_lshlrev_b64 v[28:29], 12, v[28:29]
	v_lshl_add_u64 v[28:29], v[34:35], 0, v[28:29]
	global_store_dwordx4 v[28:29], v[24:27], off

; DI void epi_slab(const GemmCfg c, const f32x16 (&acc)[4], float* sW, const float* rss, const size_t row0, const int g, const int lane,
;                  float* const g_h, u16* const g_hb, float* const g_out, const int final_out) {
;     ...
;     const int c4 = l31 * 4;
;     const int col = g * 128 + c4;
;     const float sc = (K == DFF ? 0.5f : 1.f);
; #pragma unroll
;     for (int hb_ = 0; hb_ < 2; ++hb_) {
;       f32x4 hv[8];
; #pragma unroll
;       for (int i8 = 0; i8 < 8; ++i8) hv[i8] = *(const f32x4*)(g_h + (row0 + hh + 2 * (hb_ * 8 + i8)) * D + col);
; #pragma unroll
;       for (int i8 = 0; i8 < 8; ++i8) {
;         const int r = hh + 2 * (hb_ * 8 + i8);
;         const size_t row = row0 + r;
;         f32x4 v = *(const f32x4*)(sW + r * 132 + c4);
;         f32x4 o = hv[i8] + v * sc;
;         *(f32x4*)(g_h + row * D + col) = o;
;         *(u32x2*)(g_hb + row * D + col) = MK2(pack2(o[0], o[1]), pack2(o[2], o[3]));
;         if (final_out) {
;           const int b = (int)(row / T), t = (int)(row % T);
;           if (t >= 16) *(f32x4*)(g_out + ((size_t)b * 2048 + (t - 16)) * D + col) = o;
;         }
;       }
.LBB0_322:
	ds_read_b128 v[26:29], v42 offset:9504
	v_add_u32_e32 v24, 20, v64
	v_ashrrev_i32_e32 v25, 31, v24
	v_lshl_add_u64 v[24:25], s[6:7], 0, v[24:25]
	v_mov_b32_e32 v171, v170
	s_waitcnt vmcnt(11) lgkmcnt(0)
	v_pk_fma_f32 v[20:21], v[172:173], v[26:27], v[20:21]
	v_lshlrev_b64 v[26:27], 12, v[24:25]
	v_pk_fma_f32 v[22:23], v[170:171], v[28:29], v[22:23]
	v_lshl_add_u64 v[26:27], v[32:33], 0, v[26:27]
	v_lshlrev_b64 v[28:29], 11, v[24:25]
	global_store_dwordx4 v[26:27], v[20:23], off nt
	v_cvt_pk_bf16_f32 v26, v20, v21
	v_cvt_pk_bf16_f32 v27, v22, v23
	v_lshrrev_b32_e32 v142, 5, v28
	v_lshl_add_u64 v[28:29], v[36:37], 0, v[28:29]
	s_and_b64 vcc, exec, s[44:45]
	global_store_dwordx2 v[28:29], v[26:27], off
	v_mov_b32_e32 v141, 0
	v_dot2c_f32_bf16_e32 v141, v26, v26
	v_dot2c_f32_bf16_e32 v141, v27, v27
	s_nop 4
	v_add_f32_dpp v141, v141, v141 quad_perm:[1,0,3,2] row_mask:0xf bank_mask:0xf
	s_nop 1
	v_add_f32_dpp v141, v141, v141 quad_perm:[2,3,0,1] row_mask:0xf bank_mask:0xf
	s_nop 1
	v_add_f32_dpp v141, v141, v141 row_half_mirror row_mask:0xf bank_mask:0xf
	s_nop 1
	v_add_f32_dpp v141, v141, v141 row_mirror row_mask:0xf bank_mask:0xf
	v_lshl_add_u64 v[144:145], v[142:143], 0, v[146:147]
	global_store_dword v[144:145], v141, off
	s_cbranch_vccnz .LBB0_326
	s_mov_b32 s8, 0xe03f80ff
	v_mul_hi_u32 v164, v24, s8
	v_mad_u64_u32 v[26:27], s[8:9], v25, s8, v[164:165]
	v_mov_b32_e32 v164, v27
	v_mov_b32_e32 v27, v165
	s_mov_b32 s14, 0xfe03f80f
	v_mad_u64_u32 v[26:27], s[8:9], v24, s14, v[26:27]
	v_mov_b32_e32 v26, v27
	v_mov_b32_e32 v27, v165
	v_lshl_add_u64 v[26:27], v[164:165], 0, v[26:27]
	v_mad_u64_u32 v[26:27], s[8:9], v25, s14, v[26:27]
	v_alignbit_b32 v28, v27, v26, 11
	s_movk_i32 s14, 0x810
	v_mad_u64_u32 v[28:29], s[8:9], v28, s14, 0
	v_lshrrev_b32_e32 v30, 11, v27
	v_mad_u32_u24 v29, v30, s14, v29
	v_sub_co_u32_e32 v24, vcc, v24, v28
	s_nop 1
	v_subb_co_u32_e32 v25, vcc, v25, v29, vcc
	v_cmp_lt_u64_e32 vcc, 15, v[24:25]
	s_and_saveexec_b64 s[8:9], vcc
	s_cbranch_execz .LBB0_325
	v_lshrrev_b64 v[26:27], 11, v[26:27]
	v_mov_b32_e32 v28, v165
	v_mov_b32_e32 v29, v26
	v_ashrrev_i64 v[26:27], 21, v[28:29]
	v_add_u32_e32 v164, -16, v24
	v_lshl_add_u64 v[24:25], v[26:27], 0, v[164:165]
	v_lshlrev_b64 v[24:25], 12, v[24:25]
	v_lshl_add_u64 v[24:25], v[34:35], 0, v[24:25]
	global_store_dwordx4 v[24:25], v[20:23], off

; DI void epi_slab(const GemmCfg c, const f32x16 (&acc)[4], float* sW, const float* rss, const size_t row0, const int g, const int lane,
;                  float* const g_h, u16* const g_hb, float* const g_out, const int final_out) {
;     ...
;     const int c4 = l31 * 4;
;     const int col = g * 128 + c4;
;     const float sc = (K == DFF ? 0.5f : 1.f);
; #pragma unroll
;     for (int hb_ = 0; hb_ < 2; ++hb_) {
;       f32x4 hv[8];
; #pragma unroll
;       for (int i8 = 0; i8 < 8; ++i8) hv[i8] = *(const f32x4*)(g_h + (row0 + hh + 2 * (hb_ * 8 + i8)) * D + col);
; #pragma unroll
;       for (int i8 = 0; i8 < 8; ++i8) {
;         const int r = hh + 2 * (hb_ * 8 + i8);
;         const size_t row = row0 + r;
;         f32x4 v = *(const f32x4*)(sW + r * 132 + c4);
;         f32x4 o = hv[i8] + v * sc;
;         *(f32x4*)(g_h + row * D + col) = o;
;         *(u32x2*)(g_hb + row * D + col) = MK2(pack2(o[0], o[1]), pack2(o[2], o[3]));
;         if (final_out) {
;           const int b = (int)(row / T), t = (int)(row % T);
;           if (t >= 16) *(f32x4*)(g_out + ((size_t)b * 2048 + (t - 16)) * D + col) = o;
;         }
;       }
.LBB0_326:
	ds_read_b128 v[22:25], v42 offset:10560
	v_add_u32_e32 v20, 22, v64
	v_ashrrev_i32_e32 v21, 31, v20
	v_lshl_add_u64 v[20:21], s[6:7], 0, v[20:21]
	s_and_b64 vcc, exec, s[44:45]
	s_waitcnt vmcnt(13) lgkmcnt(0)
	v_pk_fma_f32 v[16:17], v[172:173], v[22:23], v[16:17]
	v_lshlrev_b64 v[22:23], 12, v[20:21]
	v_pk_fma_f32 v[18:19], v[170:171], v[24:25], v[18:19]
	v_lshl_add_u64 v[22:23], v[32:33], 0, v[22:23]
	v_lshlrev_b64 v[24:25], 11, v[20:21]
	global_store_dwordx4 v[22:23], v[16:19], off nt
	v_cvt_pk_bf16_f32 v22, v16, v17
	v_cvt_pk_bf16_f32 v23, v18, v19
	v_lshrrev_b32_e32 v142, 5, v24
	v_lshl_add_u64 v[24:25], v[36:37], 0, v[24:25]
	global_store_dwordx2 v[24:25], v[22:23], off
	v_mov_b32_e32 v141, 0
	v_dot2c_f32_bf16_e32 v141, v22, v22
	v_dot2c_f32_bf16_e32 v141, v23, v23
	s_nop 4
	v_add_f32_dpp v141, v141, v141 quad_perm:[1,0,3,2] row_mask:0xf bank_mask:0xf
	s_nop 1
	v_add_f32_dpp v141, v141, v141 quad_perm:[2,3,0,1] row_mask:0xf bank_mask:0xf
	s_nop 1
	v_add_f32_dpp v141, v141, v141 row_half_mirror row_mask:0xf bank_mask:0xf
	s_nop 1
	v_add_f32_dpp v141, v141, v141 row_mirror row_mask:0xf bank_mask:0xf
	v_lshl_add_u64 v[144:145], v[142:143], 0, v[146:147]
	global_store_dword v[144:145], v141, off
	s_cbranch_vccnz .LBB0_330
	s_mov_b32 s8, 0xe03f80ff
	v_mul_hi_u32 v164, v20, s8
	v_mad_u64_u32 v[22:23], s[8:9], v21, s8, v[164:165]
	v_mov_b32_e32 v164, v23
	v_mov_b32_e32 v23, v165
	s_mov_b32 s14, 0xfe03f80f
	v_mad_u64_u32 v[22:23], s[8:9], v20, s14, v[22:23]
	v_mov_b32_e32 v22, v23
	v_mov_b32_e32 v23, v165
	v_lshl_add_u64 v[22:23], v[164:165], 0, v[22:23]
	v_mad_u64_u32 v[22:23], s[8:9], v21, s14, v[22:23]
	v_alignbit_b32 v24, v23, v22, 11
	s_movk_i32 s14, 0x810
	v_mad_u64_u32 v[24:25], s[8:9], v24, s14, 0
	v_lshrrev_b32_e32 v26, 11, v23
	v_mad_u32_u24 v25, v26, s14, v25
	v_sub_co_u32_e32 v20, vcc, v20, v24
	s_nop 1
	v_subb_co_u32_e32 v21, vcc, v21, v25, vcc
	v_cmp_lt_u64_e32 vcc, 15, v[20:21]
	s_and_saveexec_b64 s[8:9], vcc
	s_cbranch_execz .LBB0_329
	v_lshrrev_b64 v[22:23], 11, v[22:23]
	v_mov_b32_e32 v24, v165
	v_mov_b32_e32 v25, v22
	v_ashrrev_i64 v[22:23], 21, v[24:25]
	v_add_u32_e32 v164, -16, v20
	v_lshl_add_u64 v[20:21], v[22:23], 0, v[164:165]
	v_lshlrev_b64 v[20:21], 12, v[20:21]
	v_lshl_add_u64 v[20:21], v[34:35], 0, v[20:21]
	global_store_dwordx4 v[20:21], v[16:19], off

; DI void epi_slab(const GemmCfg c, const f32x16 (&acc)[4], float* sW, const float* rss, const size_t row0, const int g, const int lane,
;                  float* const g_h, u16* const g_hb, float* const g_out, const int final_out) {
;     ...
;     const int c4 = l31 * 4;
;     const int col = g * 128 + c4;
;     const float sc = (K == DFF ? 0.5f : 1.f);
; #pragma unroll
;     for (int hb_ = 0; hb_ < 2; ++hb_) {
;       f32x4 hv[8];
; #pragma unroll
;       for (int i8 = 0; i8 < 8; ++i8) hv[i8] = *(const f32x4*)(g_h + (row0 + hh + 2 * (hb_ * 8 + i8)) * D + col);
; #pragma unroll
;       for (int i8 = 0; i8 < 8; ++i8) {
;         const int r = hh + 2 * (hb_ * 8 + i8);
;         const size_t row = row0 + r;
;         f32x4 v = *(const f32x4*)(sW + r * 132 + c4);
;         f32x4 o = hv[i8] + v * sc;
;         *(f32x4*)(g_h + row * D + col) = o;
;         *(u32x2*)(g_hb + row * D + col) = MK2(pack2(o[0], o[1]), pack2(o[2], o[3]));
;         if (final_out) {
;           const int b = (int)(row / T), t = (int)(row % T);
;           if (t >= 16) *(f32x4*)(g_out + ((size_t)b * 2048 + (t - 16)) * D + col) = o;
;         }
;       }
.LBB0_330:
	ds_read_b128 v[18:21], v42 offset:11616
	v_add_u32_e32 v16, 24, v64
	v_ashrrev_i32_e32 v17, 31, v16
	v_lshl_add_u64 v[16:17], s[6:7], 0, v[16:17]
	v_mov_b32_e32 v171, v170
	s_waitcnt vmcnt(15) lgkmcnt(0)
	v_pk_fma_f32 v[12:13], v[172:173], v[18:19], v[12:13]
	v_lshlrev_b64 v[18:19], 12, v[16:17]
	v_pk_fma_f32 v[14:15], v[170:171], v[20:21], v[14:15]
	v_lshl_add_u64 v[18:19], v[32:33], 0, v[18:19]
	v_lshlrev_b64 v[20:21], 11, v[16:17]
	global_store_dwordx4 v[18:19], v[12:15], off nt
	v_cvt_pk_bf16_f32 v18, v12, v13
	v_cvt_pk_bf16_f32 v19, v14, v15
	v_lshrrev_b32_e32 v142, 5, v20
	v_lshl_add_u64 v[20:21], v[36:37], 0, v[20:21]
	s_and_b64 vcc, exec, s[44:45]
	global_store_dwordx2 v[20:21], v[18:19], off
	v_mov_b32_e32 v141, 0
	v_dot2c_f32_bf16_e32 v141, v18, v18
	v_dot2c_f32_bf16_e32 v141, v19, v19
	s_nop 4
	v_add_f32_dpp v141, v141, v141 quad_perm:[1,0,3,2] row_mask:0xf bank_mask:0xf
	s_nop 1
	v_add_f32_dpp v141, v141, v141 quad_perm:[2,3,0,1] row_mask:0xf bank_mask:0xf
	s_nop 1
	v_add_f32_dpp v141, v141, v141 row_half_mirror row_mask:0xf bank_mask:0xf
	s_nop 1
	v_add_f32_dpp v141, v141, v141 row_mirror row_mask:0xf bank_mask:0xf
	v_lshl_add_u64 v[144:145], v[142:143], 0, v[146:147]
	global_store_dword v[144:145], v141, off
	s_cbranch_vccnz .LBB0_334
	s_mov_b32 s8, 0xe03f80ff
	v_mul_hi_u32 v164, v16, s8
	v_mad_u64_u32 v[18:19], s[8:9], v17, s8, v[164:165]
	v_mov_b32_e32 v164, v19
	v_mov_b32_e32 v19, v165
	s_mov_b32 s14, 0xfe03f80f
	v_mad_u64_u32 v[18:19], s[8:9], v16, s14, v[18:19]
	v_mov_b32_e32 v18, v19
	v_mov_b32_e32 v19, v165
	v_lshl_add_u64 v[18:19], v[164:165], 0, v[18:19]
	v_mad_u64_u32 v[18:19], s[8:9], v17, s14, v[18:19]
	v_alignbit_b32 v20, v19, v18, 11
	s_movk_i32 s14, 0x810
	v_mad_u64_u32 v[20:21], s[8:9], v20, s14, 0
	v_lshrrev_b32_e32 v22, 11, v19
	v_mad_u32_u24 v21, v22, s14, v21
	v_sub_co_u32_e32 v16, vcc, v16, v20
	s_nop 1
	v_subb_co_u32_e32 v17, vcc, v17, v21, vcc
	v_cmp_lt_u64_e32 vcc, 15, v[16:17]
	s_and_saveexec_b64 s[8:9], vcc
	s_cbranch_execz .LBB0_333
	v_lshrrev_b64 v[18:19], 11, v[18:19]
	v_mov_b32_e32 v20, v165
	v_mov_b32_e32 v21, v18
	v_ashrrev_i64 v[18:19], 21, v[20:21]
	v_add_u32_e32 v164, -16, v16
	v_lshl_add_u64 v[16:17], v[18:19], 0, v[164:165]
	v_lshlrev_b64 v[16:17], 12, v[16:17]
	v_lshl_add_u64 v[16:17], v[34:35], 0, v[16:17]
	global_store_dwordx4 v[16:17], v[12:15], off

; DI void epi_slab(const GemmCfg c, const f32x16 (&acc)[4], float* sW, const float* rss, const size_t row0, const int g, const int lane,
;                  float* const g_h, u16* const g_hb, float* const g_out, const int final_out) {
;     ...
;     const int c4 = l31 * 4;
;     const int col = g * 128 + c4;
;     const float sc = (K == DFF ? 0.5f : 1.f);
; #pragma unroll
;     for (int hb_ = 0; hb_ < 2; ++hb_) {
;       f32x4 hv[8];
; #pragma unroll
;       for (int i8 = 0; i8 < 8; ++i8) hv[i8] = *(const f32x4*)(g_h + (row0 + hh + 2 * (hb_ * 8 + i8)) * D + col);
; #pragma unroll
;       for (int i8 = 0; i8 < 8; ++i8) {
;         const int r = hh + 2 * (hb_ * 8 + i8);
;         const size_t row = row0 + r;
;         f32x4 v = *(const f32x4*)(sW + r * 132 + c4);
;         f32x4 o = hv[i8] + v * sc;
;         *(f32x4*)(g_h + row * D + col) = o;
;         *(u32x2*)(g_hb + row * D + col) = MK2(pack2(o[0], o[1]), pack2(o[2], o[3]));
;         if (final_out) {
;           const int b = (int)(row / T), t = (int)(row % T);
;           if (t >= 16) *(f32x4*)(g_out + ((size_t)b * 2048 + (t - 16)) * D + col) = o;
;         }
;       }
.LBB0_334:
	ds_read_b128 v[14:17], v42 offset:12672
	v_add_u32_e32 v12, 26, v64
	v_ashrrev_i32_e32 v13, 31, v12
	v_lshl_add_u64 v[12:13], s[6:7], 0, v[12:13]
	s_and_b64 vcc, exec, s[44:45]
	s_waitcnt vmcnt(17) lgkmcnt(0)
	v_pk_fma_f32 v[8:9], v[172:173], v[14:15], v[8:9]
	v_lshlrev_b64 v[14:15], 12, v[12:13]
	v_pk_fma_f32 v[10:11], v[170:171], v[16:17], v[10:11]
	v_lshl_add_u64 v[14:15], v[32:33], 0, v[14:15]
	v_lshlrev_b64 v[16:17], 11, v[12:13]
	global_store_dwordx4 v[14:15], v[8:11], off nt
	v_cvt_pk_bf16_f32 v14, v8, v9
	v_cvt_pk_bf16_f32 v15, v10, v11
	v_lshrrev_b32_e32 v142, 5, v16
	v_lshl_add_u64 v[16:17], v[36:37], 0, v[16:17]
	global_store_dwordx2 v[16:17], v[14:15], off
	v_mov_b32_e32 v141, 0
	v_dot2c_f32_bf16_e32 v141, v14, v14
	v_dot2c_f32_bf16_e32 v141, v15, v15
	s_nop 4
	v_add_f32_dpp v141, v141, v141 quad_perm:[1,0,3,2] row_mask:0xf bank_mask:0xf
	s_nop 1
	v_add_f32_dpp v141, v141, v141 quad_perm:[2,3,0,1] row_mask:0xf bank_mask:0xf
	s_nop 1
	v_add_f32_dpp v141, v141, v141 row_half_mirror row_mask:0xf bank_mask:0xf
	s_nop 1
	v_add_f32_dpp v141, v141, v141 row_mirror row_mask:0xf bank_mask:0xf
	v_lshl_add_u64 v[144:145], v[142:143], 0, v[146:147]
	global_store_dword v[144:145], v141, off
	s_cbranch_vccnz .LBB0_338
	s_mov_b32 s8, 0xe03f80ff
	v_mul_hi_u32 v164, v12, s8
	v_mad_u64_u32 v[14:15], s[8:9], v13, s8, v[164:165]
	v_mov_b32_e32 v164, v15
	v_mov_b32_e32 v15, v165
	s_mov_b32 s14, 0xfe03f80f
	v_mad_u64_u32 v[14:15], s[8:9], v12, s14, v[14:15]
	v_mov_b32_e32 v14, v15
	v_mov_b32_e32 v15, v165
	v_lshl_add_u64 v[14:15], v[164:165], 0, v[14:15]
	v_mad_u64_u32 v[14:15], s[8:9], v13, s14, v[14:15]
	v_alignbit_b32 v16, v15, v14, 11
	s_movk_i32 s14, 0x810
	v_mad_u64_u32 v[16:17], s[8:9], v16, s14, 0
	v_lshrrev_b32_e32 v18, 11, v15
	v_mad_u32_u24 v17, v18, s14, v17
	v_sub_co_u32_e32 v12, vcc, v12, v16
	s_nop 1
	v_subb_co_u32_e32 v13, vcc, v13, v17, vcc
	v_cmp_lt_u64_e32 vcc, 15, v[12:13]
	s_and_saveexec_b64 s[8:9], vcc
	s_cbranch_execz .LBB0_337
	v_lshrrev_b64 v[14:15], 11, v[14:15]
	v_mov_b32_e32 v16, v165
	v_mov_b32_e32 v17, v14
	v_ashrrev_i64 v[14:15], 21, v[16:17]
	v_add_u32_e32 v164, -16, v12
	v_lshl_add_u64 v[12:13], v[14:15], 0, v[164:165]
	v_lshlrev_b64 v[12:13], 12, v[12:13]
	v_lshl_add_u64 v[12:13], v[34:35], 0, v[12:13]
	global_store_dwordx4 v[12:13], v[8:11], off

; DI void epi_slab(const GemmCfg c, const f32x16 (&acc)[4], float* sW, const float* rss, const size_t row0, const int g, const int lane,
;                  float* const g_h, u16* const g_hb, float* const g_out, const int final_out) {
;     ...
;     const int c4 = l31 * 4;
;     const int col = g * 128 + c4;
;     const float sc = (K == DFF ? 0.5f : 1.f);
; #pragma unroll
;     for (int hb_ = 0; hb_ < 2; ++hb_) {
;       f32x4 hv[8];
; #pragma unroll
;       for (int i8 = 0; i8 < 8; ++i8) hv[i8] = *(const f32x4*)(g_h + (row0 + hh + 2 * (hb_ * 8 + i8)) * D + col);
; #pragma unroll
;       for (int i8 = 0; i8 < 8; ++i8) {
;         const int r = hh + 2 * (hb_ * 8 + i8);
;         const size_t row = row0 + r;
;         f32x4 v = *(const f32x4*)(sW + r * 132 + c4);
;         f32x4 o = hv[i8] + v * sc;
;         *(f32x4*)(g_h + row * D + col) = o;
;         *(u32x2*)(g_hb + row * D + col) = MK2(pack2(o[0], o[1]), pack2(o[2], o[3]));
;         if (final_out) {
;           const int b = (int)(row / T), t = (int)(row % T);
;           if (t >= 16) *(f32x4*)(g_out + ((size_t)b * 2048 + (t - 16)) * D + col) = o;
;         }
;       }
.LBB0_338:
	ds_read_b128 v[10:13], v42 offset:13728
	v_add_u32_e32 v8, 28, v64
	v_ashrrev_i32_e32 v9, 31, v8
	v_lshl_add_u64 v[8:9], s[6:7], 0, v[8:9]
	v_mov_b32_e32 v171, v170
	s_waitcnt vmcnt(19) lgkmcnt(0)
	v_pk_fma_f32 v[4:5], v[172:173], v[10:11], v[4:5]
	v_lshlrev_b64 v[10:11], 12, v[8:9]
	v_pk_fma_f32 v[6:7], v[170:171], v[12:13], v[6:7]
	v_lshl_add_u64 v[10:11], v[32:33], 0, v[10:11]
	v_lshlrev_b64 v[12:13], 11, v[8:9]
	global_store_dwordx4 v[10:11], v[4:7], off nt
	v_cvt_pk_bf16_f32 v10, v4, v5
	v_cvt_pk_bf16_f32 v11, v6, v7
	v_lshrrev_b32_e32 v142, 5, v12
	v_lshl_add_u64 v[12:13], v[36:37], 0, v[12:13]
	s_and_b64 vcc, exec, s[44:45]
	global_store_dwordx2 v[12:13], v[10:11], off
	v_mov_b32_e32 v141, 0
	v_dot2c_f32_bf16_e32 v141, v10, v10
	v_dot2c_f32_bf16_e32 v141, v11, v11
	s_nop 4
	v_add_f32_dpp v141, v141, v141 quad_perm:[1,0,3,2] row_mask:0xf bank_mask:0xf
	s_nop 1
	v_add_f32_dpp v141, v141, v141 quad_perm:[2,3,0,1] row_mask:0xf bank_mask:0xf
	s_nop 1
	v_add_f32_dpp v141, v141, v141 row_half_mirror row_mask:0xf bank_mask:0xf
	s_nop 1
	v_add_f32_dpp v141, v141, v141 row_mirror row_mask:0xf bank_mask:0xf
	v_lshl_add_u64 v[144:145], v[142:143], 0, v[146:147]
	global_store_dword v[144:145], v141, off
	s_cbranch_vccnz .LBB0_342
	s_mov_b32 s8, 0xe03f80ff
	v_mul_hi_u32 v164, v8, s8
	v_mad_u64_u32 v[10:11], s[8:9], v9, s8, v[164:165]
	v_mov_b32_e32 v164, v11
	v_mov_b32_e32 v11, v165
	s_mov_b32 s14, 0xfe03f80f
	v_mad_u64_u32 v[10:11], s[8:9], v8, s14, v[10:11]
	v_mov_b32_e32 v10, v11
	v_mov_b32_e32 v11, v165
	v_lshl_add_u64 v[10:11], v[164:165], 0, v[10:11]
	v_mad_u64_u32 v[10:11], s[8:9], v9, s14, v[10:11]
	v_alignbit_b32 v12, v11, v10, 11
	s_movk_i32 s14, 0x810
	v_mad_u64_u32 v[12:13], s[8:9], v12, s14, 0
	v_lshrrev_b32_e32 v14, 11, v11
	v_mad_u32_u24 v13, v14, s14, v13
	v_sub_co_u32_e32 v8, vcc, v8, v12
	s_nop 1
	v_subb_co_u32_e32 v9, vcc, v9, v13, vcc
	v_cmp_lt_u64_e32 vcc, 15, v[8:9]
	s_and_saveexec_b64 s[8:9], vcc
	s_cbranch_execz .LBB0_341
	v_lshrrev_b64 v[10:11], 11, v[10:11]
	v_mov_b32_e32 v12, v165
	v_mov_b32_e32 v13, v10
	v_ashrrev_i64 v[10:11], 21, v[12:13]
	v_add_u32_e32 v164, -16, v8
	v_lshl_add_u64 v[8:9], v[10:11], 0, v[164:165]
	v_lshlrev_b64 v[8:9], 12, v[8:9]
	v_lshl_add_u64 v[8:9], v[34:35], 0, v[8:9]
	global_store_dwordx4 v[8:9], v[4:7], off

; DI void epi_slab(const GemmCfg c, const f32x16 (&acc)[4], float* sW, const float* rss, const size_t row0, const int g, const int lane,
;                  float* const g_h, u16* const g_hb, float* const g_out, const int final_out) {
;     ...
;     const int c4 = l31 * 4;
;     const int col = g * 128 + c4;
;     const float sc = (K == DFF ? 0.5f : 1.f);
; #pragma unroll
;     for (int hb_ = 0; hb_ < 2; ++hb_) {
;       f32x4 hv[8];
; #pragma unroll
;       for (int i8 = 0; i8 < 8; ++i8) hv[i8] = *(const f32x4*)(g_h + (row0 + hh + 2 * (hb_ * 8 + i8)) * D + col);
; #pragma unroll
;       for (int i8 = 0; i8 < 8; ++i8) {
;         const int r = hh + 2 * (hb_ * 8 + i8);
;         const size_t row = row0 + r;
;         f32x4 v = *(const f32x4*)(sW + r * 132 + c4);
;         f32x4 o = hv[i8] + v * sc;
;         *(f32x4*)(g_h + row * D + col) = o;
;         *(u32x2*)(g_hb + row * D + col) = MK2(pack2(o[0], o[1]), pack2(o[2], o[3]));
;         if (final_out) {
;           const int b = (int)(row / T), t = (int)(row % T);
;           if (t >= 16) *(f32x4*)(g_out + ((size_t)b * 2048 + (t - 16)) * D + col) = o;
;         }
;       }
.LBB0_342:
	ds_read_b128 v[6:9], v42 offset:14784
	v_add_u32_e32 v4, 30, v64
	v_ashrrev_i32_e32 v5, 31, v4
	v_lshl_add_u64 v[4:5], s[6:7], 0, v[4:5]
	s_and_b64 vcc, exec, s[44:45]
	s_waitcnt vmcnt(21) lgkmcnt(0)
	v_pk_fma_f32 v[0:1], v[172:173], v[6:7], v[0:1]
	v_lshlrev_b64 v[6:7], 12, v[4:5]
	v_pk_fma_f32 v[2:3], v[170:171], v[8:9], v[2:3]
	v_lshl_add_u64 v[6:7], v[32:33], 0, v[6:7]
	v_lshlrev_b64 v[8:9], 11, v[4:5]
	global_store_dwordx4 v[6:7], v[0:3], off nt
	v_cvt_pk_bf16_f32 v6, v0, v1
	v_cvt_pk_bf16_f32 v7, v2, v3
	v_lshrrev_b32_e32 v142, 5, v8
	v_lshl_add_u64 v[8:9], v[36:37], 0, v[8:9]
	global_store_dwordx2 v[8:9], v[6:7], off
	v_mov_b32_e32 v141, 0
	v_dot2c_f32_bf16_e32 v141, v6, v6
	v_dot2c_f32_bf16_e32 v141, v7, v7
	s_nop 4
	v_add_f32_dpp v141, v141, v141 quad_perm:[1,0,3,2] row_mask:0xf bank_mask:0xf
	s_nop 1
	v_add_f32_dpp v141, v141, v141 quad_perm:[2,3,0,1] row_mask:0xf bank_mask:0xf
	s_nop 1
	v_add_f32_dpp v141, v141, v141 row_half_mirror row_mask:0xf bank_mask:0xf
	s_nop 1
	v_add_f32_dpp v141, v141, v141 row_mirror row_mask:0xf bank_mask:0xf
	v_lshl_add_u64 v[144:145], v[142:143], 0, v[146:147]
	global_store_dword v[144:145], v141, off
	s_cbranch_vccnz .LBB0_346
	s_mov_b32 s6, 0xe03f80ff
	v_mul_hi_u32 v164, v4, s6
	v_mad_u64_u32 v[6:7], s[6:7], v5, s6, v[164:165]
	v_mov_b32_e32 v164, v7
	v_mov_b32_e32 v7, v165
	s_mov_b32 s8, 0xfe03f80f
	v_mad_u64_u32 v[6:7], s[6:7], v4, s8, v[6:7]
	v_mov_b32_e32 v6, v7
	v_mov_b32_e32 v7, v165
	v_lshl_add_u64 v[6:7], v[164:165], 0, v[6:7]
	v_mad_u64_u32 v[6:7], s[6:7], v5, s8, v[6:7]
	v_alignbit_b32 v8, v7, v6, 11
	s_movk_i32 s8, 0x810
	v_mad_u64_u32 v[8:9], s[6:7], v8, s8, 0
	v_lshrrev_b32_e32 v10, 11, v7
	v_mad_u32_u24 v9, v10, s8, v9
	v_sub_co_u32_e32 v4, vcc, v4, v8
	s_nop 1
	v_subb_co_u32_e32 v5, vcc, v5, v9, vcc
	v_cmp_lt_u64_e32 vcc, 15, v[4:5]
	s_and_saveexec_b64 s[6:7], vcc
	s_cbranch_execz .LBB0_345
	v_lshrrev_b64 v[6:7], 11, v[6:7]
	v_mov_b32_e32 v8, v165
	v_mov_b32_e32 v9, v6
	v_ashrrev_i64 v[6:7], 21, v[8:9]
	v_add_u32_e32 v164, -16, v4
	v_lshl_add_u64 v[4:5], v[6:7], 0, v[164:165]
	v_lshlrev_b64 v[4:5], 12, v[4:5]
	v_lshl_add_u64 v[4:5], v[34:35], 0, v[4:5]
	global_store_dwordx4 v[4:5], v[0:3], off
